# gemm256 mainloop hand-pipelined with LDS-DMA staging (swizzled LDS, fragment prefetch) at gateup/down/inproj sites + attention loop v2
# speedup vs baseline: 1.1042x; 1.0222x over previous
; DI int tid512() { int t = threadIdx.x; asm volatile("" : "+v"(t)); return t; }
; DI unsigned voff256(size_t ld) { const int t = tid512(); return (unsigned)(((size_t)(t >> 3) * ld + (t & 7) * 8) * 2); }
; DI void gemm256(const char* a_u, unsigned a_voff, size_t astep, const char* b_u, unsigned b_voff, size_t bstep, int nk, char* smem, f32x16 (&acc)[4][2]) {
;   asm volatile("" : "+s"(nk));
;   const int t = tid512(), lane = t & 63, w = t >> 6, wm = w >> 2, wn = w & 3, r = lane & 31, h = lane >> 5;
;   const int soff = (t >> 3) * LROW + (t & 7) * 16;
;   const int aoff = (128 * wm + r) * LROW + h * 16, boff = T2 + (64 * wn + r) * LROW + h * 16;
;   u32x4 ra[4], rb[4];
; #pragma unroll
;   for (int i = 0; i < 4; ++i) { ra[i] = *(const u32x4*)(a_u + i * astep + a_voff); rb[i] = *(const u32x4*)(b_u + i * bstep + b_voff); }
;   __syncthreads();
; #pragma unroll
;   for (int i = 0; i < 4; ++i) { *(u32x4*)(smem + soff + i * 64 * LROW) = ra[i]; *(u32x4*)(smem + T2 + soff + i * 64 * LROW) = rb[i]; }
;   const int last = nk - 1;
;   {
;     const int k1 = last < 1 ? last : 1;
; #pragma unroll
;     for (int i = 0; i < 4; ++i) { ra[i] = *(const u32x4*)(a_u + i * astep + k1 * 128 + a_voff); rb[i] = *(const u32x4*)(b_u + i * bstep + k1 * 128 + b_voff); }
;   }
;   __syncthreads();
; DI void inproj_phase(const Params& p, int layer, char* smem) {
;     ...
;   for (int i = 0;; ++i) {
;     const int L = tile_of(i, 32 * 24);
;     if (L < 0) break;
;     int tm, tn; tile_mn(L, 32, 24, tm, tn);
;     f32x16 acc[4][2]; zero_acc256(acc);
;     gemm256((const char*)(W + (size_t)(tn * 256) * DM), voff256(DM), (size_t)128 * DM, (const char*)(H + (size_t)(256 + tm * 256) * DM), voff256(DM), (size_t)128 * DM, DM / 64, smem, acc);
.LBB0_188:
	s_mul_hi_u32 s6, s8, 0xaaaaaaab
	s_lshr_b32 s6, s6, 6
	s_lshl_b32 s9, s6, 2
	s_sub_i32 s7, 32, s9
	s_min_i32 s10, s7, 4
	s_abs_i32 s7, s10
	v_cvt_f32_u32_e32 v2, s7
	s_sub_i32 s12, 0, s7
	s_mulk_i32 s6, 0xffa0
	s_add_i32 s6, s6, s8
	v_rcp_iflag_f32_e32 v2, v2
	s_abs_i32 s8, s6
	s_xor_b32 s11, s6, s10
	s_ashr_i32 s11, s11, 31
	v_mul_f32_e32 v2, 0x4f7ffffe, v2
	v_cvt_u32_f32_e32 v2, v2
	s_movk_i32 s16, 0xf000
	v_mov_b32_e32 v37, v181
	v_readfirstlane_b32 s13, v2
	s_mul_i32 s12, s12, s13
	s_mul_hi_u32 s12, s13, s12
	s_add_i32 s13, s13, s12
	s_mul_hi_u32 s12, s8, s13
	s_mul_i32 s13, s12, s7
	s_sub_i32 s8, s8, s13
	s_add_i32 s14, s12, 1
	s_sub_i32 s13, s8, s7
	s_cmp_ge_u32 s8, s7
	s_cselect_b32 s12, s14, s12
	s_cselect_b32 s8, s13, s8
	s_add_i32 s13, s12, 1
	s_cmp_ge_u32 s8, s7
	s_cselect_b32 s7, s13, s12
	s_xor_b32 s7, s7, s11
	s_sub_i32 s7, s7, s11
	s_mul_i32 s10, s7, s10
	s_lshl_b32 s8, s7, 8
	s_sub_i32 s6, s6, s10
	s_add_i32 s6, s6, s9
	s_ashr_i32 s9, s8, 31
	s_lshl_b64 s[8:9], s[8:9], 12
	s_add_u32 s12, s0, s8
	v_mov_b32_e32 v2, v0
	s_addc_u32 s13, s1, s9
	s_lshl_b32 s6, s6, 8
	v_lshlrev_b32_e32 v3, 4, v2
	v_and_b32_e32 v3, 0x70, v3
	v_lshlrev_b32_e32 v2, 9, v2
	s_add_i32 s8, s6, 0x100
	v_and_or_b32 v180, v2, s16, v3
	s_ashr_i32 s9, s8, 31
	v_mov_b32_e32 v2, v0
	s_lshl_b64 s[10:11], s[8:9], 12
	s_add_u32 s14, s92, s10
	v_lshlrev_b32_e32 v3, 4, v2
	v_and_b32_e32 v3, 0x70, v3
	v_lshlrev_b32_e32 v2, 9, v2
	v_lshl_add_u64 v[162:163], s[12:13], 0, v[180:181]
	s_addc_u32 s15, s93, s11
	v_and_or_b32 v36, v2, s16, v3
	v_add_co_u32_e32 v12, vcc, s84, v162
	v_lshl_add_u64 v[164:165], s[14:15], 0, v[36:37]
	s_nop 0
	v_addc_co_u32_e32 v13, vcc, 0, v163, vcc
	v_add_co_u32_e32 v16, vcc, s84, v164
	s_mov_b32 s9, 32
	s_nop 0
	v_addc_co_u32_e32 v17, vcc, 0, v165, vcc
	v_add_co_u32_e32 v20, vcc, s31, v162
	s_add_i32 s10, s9, -1
	s_nop 0
	v_addc_co_u32_e32 v21, vcc, 0, v163, vcc
	s_min_i32 s11, s10, 1
	v_add_co_u32_e32 v24, vcc, s31, v164
	s_lshl_b32 s11, s11, 7
	v_mov_b32_e32 v2, v0
	v_addc_co_u32_e32 v25, vcc, 0, v165, vcc
	s_ashr_i32 s16, s11, 31
	v_lshrrev_b32_e32 v132, 6, v0
	s_nop 0
	v_readfirstlane_b32 s61, v132
	v_and_b32_e32 v132, 63, v0
	v_and_b32_e32 v133, 31, v132
	v_lshrrev_b32_e32 v136, 5, v132
	v_bfe_u32 v137, v133, 1, 3
	v_lshlrev_b32_e32 v133, 7, v133
	s_lshr_b32 s60, s61, 2
	s_lshl_b32 s60, s60, 14
	s_add_i32 s60, s60, 16
	s_and_b32 s62, s61, 3
	s_lshl_b32 s62, s62, 13
	s_add_i32 s62, s62, 0x10010
	v_add_u32_e32 v194, 0, v136
	v_xor_b32_e32 v194, v194, v137
	v_lshl_add_u32 v194, v194, 4, v133
	v_add_u32_e32 v160, s62, v194
	v_add_u32_e32 v194, s60, v194
	v_add_u32_e32 v195, 2, v136
	v_xor_b32_e32 v195, v195, v137
	v_lshl_add_u32 v195, v195, 4, v133
	v_add_u32_e32 v161, s62, v195
	v_add_u32_e32 v195, s60, v195
	v_add_u32_e32 v250, 4, v136
	v_xor_b32_e32 v250, v250, v137
	v_lshl_add_u32 v250, v250, 4, v133
	v_add_u32_e32 v162, s62, v250
	v_add_u32_e32 v250, s60, v250
	v_add_u32_e32 v251, 6, v136
	v_xor_b32_e32 v251, v251, v137
	v_lshl_add_u32 v251, v251, 4, v133
	v_add_u32_e32 v163, s62, v251
	v_add_u32_e32 v251, s60, v251
	v_lshrrev_b32_e32 v133, 3, v132
	s_mov_b32 s60, 0x1000
	v_mul_lo_u32 v133, v133, s60
	v_and_b32_e32 v136, 7, v132
	v_lshrrev_b32_e32 v137, 4, v132
	v_xor_b32_e32 v164, v137, v136
	v_lshl_add_u32 v164, v164, 4, v133
	v_add_u32_e32 v165, 4, v137
	v_xor_b32_e32 v165, v165, v136
	v_lshl_add_u32 v165, v165, 4, v133
	v_add_u32_e32 v165, 0x8000, v165
	v_xor_b32_e32 v130, v137, v136
	v_lshl_add_u32 v130, v130, 4, v133
	v_add_u32_e32 v130, 0x10000, v130
	v_add_u32_e32 v131, 4, v137
	v_xor_b32_e32 v131, v131, v136
	v_lshl_add_u32 v131, v131, 4, v133
	v_add_u32_e32 v131, 0x18000, v131
	s_mul_i32 s60, s61, 0x20000
	s_add_u32 s52, s12, s60
	s_addc_u32 s53, s13, 0
	s_add_u32 s54, s14, s60
	s_addc_u32 s55, s15, 0
	s_lshl_b32 s58, s61, 12
	s_add_i32 s58, s58, 16
	s_add_i32 s59, s58, 0x10000
	s_mov_b32 s56, 0
	s_mov_b32 s57, 31
	s_barrier
	s_add_u32 m0, s58, 0x0
	s_nop 0
	global_load_lds_dwordx4 v164, s[52:53]
	s_add_u32 m0, s58, 0x400
	s_nop 0
	global_load_lds_dwordx4 v165, s[52:53]
	s_add_u32 m0, s58, 0x800
	s_nop 0
	global_load_lds_dwordx4 v130, s[52:53]
	s_add_u32 m0, s58, 0xc00
	s_nop 0
	global_load_lds_dwordx4 v131, s[52:53]
	s_add_u32 m0, s59, 0x0
	s_nop 0
	global_load_lds_dwordx4 v164, s[54:55]
	s_add_u32 m0, s59, 0x400
	s_nop 0
	global_load_lds_dwordx4 v165, s[54:55]
	s_add_u32 m0, s59, 0x800
	s_nop 0
	global_load_lds_dwordx4 v130, s[54:55]
	s_add_u32 m0, s59, 0xc00
	s_nop 0
	global_load_lds_dwordx4 v131, s[54:55]
	s_cmp_lt_u32 s56, s57
	s_cselect_b32 s60, 0x80, 0
	s_add_u32 s52, s52, s60
	s_addc_u32 s53, s53, 0
	s_add_u32 s54, s54, s60
	s_addc_u32 s55, s55, 0
	v_mov_b64_e32 v[114:115], 0
	v_mov_b64_e32 v[116:117], 0
	v_mov_b64_e32 v[118:119], 0
	v_mov_b64_e32 v[120:121], 0
	v_mov_b64_e32 v[122:123], 0
	v_mov_b64_e32 v[124:125], 0
	v_mov_b64_e32 v[126:127], 0
	v_mov_b64_e32 v[128:129], 0
	v_mov_b64_e32 v[50:51], 0
	v_mov_b64_e32 v[52:53], 0
	v_mov_b64_e32 v[54:55], 0
	v_mov_b64_e32 v[56:57], 0
	v_mov_b64_e32 v[58:59], 0
	v_mov_b64_e32 v[60:61], 0
	v_mov_b64_e32 v[62:63], 0
	v_mov_b64_e32 v[64:65], 0
	v_mov_b64_e32 v[98:99], 0
	v_mov_b64_e32 v[100:101], 0
	v_mov_b64_e32 v[102:103], 0
	v_mov_b64_e32 v[104:105], 0
	v_mov_b64_e32 v[106:107], 0
	v_mov_b64_e32 v[108:109], 0
	v_mov_b64_e32 v[110:111], 0
	v_mov_b64_e32 v[112:113], 0
	v_mov_b64_e32 v[34:35], 0
	v_mov_b64_e32 v[36:37], 0
	v_mov_b64_e32 v[38:39], 0
	v_mov_b64_e32 v[40:41], 0
	v_mov_b64_e32 v[42:43], 0
	v_mov_b64_e32 v[44:45], 0
	v_mov_b64_e32 v[46:47], 0
	v_mov_b64_e32 v[48:49], 0
	v_mov_b64_e32 v[82:83], 0
	v_mov_b64_e32 v[84:85], 0
	v_mov_b64_e32 v[86:87], 0
	v_mov_b64_e32 v[88:89], 0
	v_mov_b64_e32 v[90:91], 0
	v_mov_b64_e32 v[92:93], 0
	v_mov_b64_e32 v[94:95], 0
	v_mov_b64_e32 v[96:97], 0
	v_mov_b64_e32 v[18:19], 0
	v_mov_b64_e32 v[20:21], 0
	v_mov_b64_e32 v[22:23], 0
	v_mov_b64_e32 v[24:25], 0
	v_mov_b64_e32 v[26:27], 0
	v_mov_b64_e32 v[28:29], 0
	v_mov_b64_e32 v[30:31], 0
	v_mov_b64_e32 v[32:33], 0
	v_mov_b64_e32 v[66:67], 0
	v_mov_b64_e32 v[68:69], 0
	v_mov_b64_e32 v[70:71], 0
	v_mov_b64_e32 v[72:73], 0
	v_mov_b64_e32 v[74:75], 0
	v_mov_b64_e32 v[76:77], 0
	v_mov_b64_e32 v[78:79], 0
	v_mov_b64_e32 v[80:81], 0
	v_mov_b64_e32 v[2:3], 0
	v_mov_b64_e32 v[4:5], 0
	v_mov_b64_e32 v[6:7], 0
	v_mov_b64_e32 v[8:9], 0
	v_mov_b64_e32 v[10:11], 0
	v_mov_b64_e32 v[12:13], 0
	v_mov_b64_e32 v[14:15], 0
	v_mov_b64_e32 v[16:17], 0
	s_waitcnt vmcnt(0)
	s_barrier
	ds_read_b128 v[196:199], v194 offset:0
	ds_read_b128 v[212:215], v160 offset:0
	ds_read_b128 v[216:219], v160 offset:4096
	ds_read_b128 v[200:203], v194 offset:4096
	ds_read_b128 v[204:207], v194 offset:8192
	ds_read_b128 v[208:211], v194 offset:12288
; #define MFMA32(a, b, c) __builtin_amdgcn_mfma_f32_32x32x16_bf16((a), (b), (c), 0, 0, 0)
; DI void gemm256(const char* a_u, unsigned a_voff, size_t astep, const char* b_u, unsigned b_voff, size_t bstep, int nk, char* smem, f32x16 (&acc)[4][2]) {
;     ...
;   for (int kt = 0; kt < nk; ++kt) {
;     const int cur = kt & 1, k2 = (kt + 2 < last) ? kt + 2 : last;
;     const char* S = smem + cur * 2 * T2;
;     char* D = smem + (cur ^ 1) * 2 * T2;
;     const char* an = a_u + (size_t)k2 * 128;
;     const char* bn = b_u + (size_t)k2 * 128;
; #pragma unroll
;     for (int s = 0; s < 4; ++s) {
;       bf16x8 a[4], b[2];
; #pragma unroll
;       for (int mi = 0; mi < 4; ++mi) a[mi] = *(const bf16x8*)(S + aoff + mi * 32 * LROW + s * 32);
; #pragma unroll
;       for (int ni = 0; ni < 2; ++ni) b[ni] = *(const bf16x8*)(S + boff + ni * 32 * LROW + s * 32);
;       *(u32x4*)(D + soff + s * 64 * LROW) = ra[s];
;       *(u32x4*)(D + T2 + soff + s * 64 * LROW) = rb[s];
;       ra[s] = *(const u32x4*)(an + s * astep + a_voff);
;       rb[s] = *(const u32x4*)(bn + s * bstep + b_voff);
; #pragma unroll
;       for (int mi = 0; mi < 4; ++mi)
; #pragma unroll
;         for (int ni = 0; ni < 2; ++ni) acc[mi][ni] = MFMA32(a[mi], b[ni], acc[mi][ni]);
;     }
.Lg_inproj_loop:
	s_add_i32 s56, s56, 1
	s_waitcnt lgkmcnt(0)
	v_mfma_f32_32x32x16_bf16 v[114:129], v[196:199], v[212:215], v[114:129]
	ds_read_b128 v[220:223], v195 offset:0
	ds_read_b128 v[242:245], v161 offset:0
	v_mfma_f32_32x32x16_bf16 v[50:65], v[196:199], v[216:219], v[50:65]
	ds_read_b128 v[246:249], v161 offset:4096
	ds_read_b128 v[224:227], v195 offset:4096
	v_mfma_f32_32x32x16_bf16 v[98:113], v[200:203], v[212:215], v[98:113]
	ds_read_b128 v[228:231], v195 offset:8192
	ds_read_b128 v[238:241], v195 offset:12288
	v_mfma_f32_32x32x16_bf16 v[34:49], v[200:203], v[216:219], v[34:49]
	s_add_u32 m0, s58, 0x8000
	s_nop 0
	global_load_lds_dwordx4 v164, s[52:53]
	v_mfma_f32_32x32x16_bf16 v[82:97], v[204:207], v[212:215], v[82:97]
	s_add_u32 m0, s58, 0x8400
	s_nop 0
	global_load_lds_dwordx4 v165, s[52:53]
	v_mfma_f32_32x32x16_bf16 v[18:33], v[204:207], v[216:219], v[18:33]
	s_add_u32 m0, s58, 0x8800
	s_nop 0
	global_load_lds_dwordx4 v130, s[52:53]
	v_mfma_f32_32x32x16_bf16 v[66:81], v[208:211], v[212:215], v[66:81]
	s_add_u32 m0, s58, 0x8c00
	s_nop 0
	global_load_lds_dwordx4 v131, s[52:53]
	v_mfma_f32_32x32x16_bf16 v[2:17], v[208:211], v[216:219], v[2:17]
	s_waitcnt lgkmcnt(0)
	v_mfma_f32_32x32x16_bf16 v[114:129], v[220:223], v[242:245], v[114:129]
	ds_read_b128 v[196:199], v250 offset:0
	ds_read_b128 v[212:215], v162 offset:0
	v_mfma_f32_32x32x16_bf16 v[50:65], v[220:223], v[246:249], v[50:65]
	ds_read_b128 v[216:219], v162 offset:4096
	ds_read_b128 v[200:203], v250 offset:4096
	v_mfma_f32_32x32x16_bf16 v[98:113], v[224:227], v[242:245], v[98:113]
	ds_read_b128 v[204:207], v250 offset:8192
	ds_read_b128 v[208:211], v250 offset:12288
	v_mfma_f32_32x32x16_bf16 v[34:49], v[224:227], v[246:249], v[34:49]
	s_add_u32 m0, s59, 0x8000
	s_nop 0
	global_load_lds_dwordx4 v164, s[54:55]
	v_mfma_f32_32x32x16_bf16 v[82:97], v[228:231], v[242:245], v[82:97]
	s_add_u32 m0, s59, 0x8400
	s_nop 0
	global_load_lds_dwordx4 v165, s[54:55]
	v_mfma_f32_32x32x16_bf16 v[18:33], v[228:231], v[246:249], v[18:33]
	s_add_u32 m0, s59, 0x8800
	s_nop 0
	global_load_lds_dwordx4 v130, s[54:55]
	v_mfma_f32_32x32x16_bf16 v[66:81], v[238:241], v[242:245], v[66:81]
	s_add_u32 m0, s59, 0x8c00
	s_nop 0
	global_load_lds_dwordx4 v131, s[54:55]
	v_mfma_f32_32x32x16_bf16 v[2:17], v[238:241], v[246:249], v[2:17]
	s_waitcnt lgkmcnt(0)
	v_mfma_f32_32x32x16_bf16 v[114:129], v[196:199], v[212:215], v[114:129]
	ds_read_b128 v[220:223], v251 offset:0
	ds_read_b128 v[242:245], v163 offset:0
	v_mfma_f32_32x32x16_bf16 v[50:65], v[196:199], v[216:219], v[50:65]
	ds_read_b128 v[246:249], v163 offset:4096
	ds_read_b128 v[224:227], v251 offset:4096
	v_mfma_f32_32x32x16_bf16 v[98:113], v[200:203], v[212:215], v[98:113]
	ds_read_b128 v[228:231], v251 offset:8192
	ds_read_b128 v[238:241], v251 offset:12288
	v_mfma_f32_32x32x16_bf16 v[34:49], v[200:203], v[216:219], v[34:49]
	s_cmp_lt_u32 s56, s57
	s_cselect_b32 s60, 0x80, 0
	s_add_u32 s52, s52, s60
	s_addc_u32 s53, s53, 0
	s_add_u32 s54, s54, s60
	s_addc_u32 s55, s55, 0
	v_mfma_f32_32x32x16_bf16 v[82:97], v[204:207], v[212:215], v[82:97]
	v_mfma_f32_32x32x16_bf16 v[18:33], v[204:207], v[216:219], v[18:33]
	v_mfma_f32_32x32x16_bf16 v[66:81], v[208:211], v[212:215], v[66:81]
	v_mfma_f32_32x32x16_bf16 v[2:17], v[208:211], v[216:219], v[2:17]
	s_waitcnt lgkmcnt(0)
	v_mfma_f32_32x32x16_bf16 v[114:129], v[220:223], v[242:245], v[114:129]
	v_mfma_f32_32x32x16_bf16 v[50:65], v[220:223], v[246:249], v[50:65]
	v_mfma_f32_32x32x16_bf16 v[98:113], v[224:227], v[242:245], v[98:113]
	v_mfma_f32_32x32x16_bf16 v[34:49], v[224:227], v[246:249], v[34:49]
	v_mfma_f32_32x32x16_bf16 v[82:97], v[228:231], v[242:245], v[82:97]
	v_mfma_f32_32x32x16_bf16 v[18:33], v[228:231], v[246:249], v[18:33]
	v_mfma_f32_32x32x16_bf16 v[66:81], v[238:241], v[242:245], v[66:81]
	v_mfma_f32_32x32x16_bf16 v[2:17], v[238:241], v[246:249], v[2:17]
	s_waitcnt vmcnt(0)
	s_barrier
; #define MFMA32(a, b, c) __builtin_amdgcn_mfma_f32_32x32x16_bf16((a), (b), (c), 0, 0, 0)
; DI void gemm256(const char* a_u, unsigned a_voff, size_t astep, const char* b_u, unsigned b_voff, size_t bstep, int nk, char* smem, f32x16 (&acc)[4][2]) {
;     ...
;   for (int kt = 0; kt < nk; ++kt) {
;     const int cur = kt & 1, k2 = (kt + 2 < last) ? kt + 2 : last;
;     const char* S = smem + cur * 2 * T2;
;     char* D = smem + (cur ^ 1) * 2 * T2;
;     const char* an = a_u + (size_t)k2 * 128;
;     const char* bn = b_u + (size_t)k2 * 128;
; #pragma unroll
;     for (int s = 0; s < 4; ++s) {
;       bf16x8 a[4], b[2];
; #pragma unroll
;       for (int mi = 0; mi < 4; ++mi) a[mi] = *(const bf16x8*)(S + aoff + mi * 32 * LROW + s * 32);
; #pragma unroll
;       for (int ni = 0; ni < 2; ++ni) b[ni] = *(const bf16x8*)(S + boff + ni * 32 * LROW + s * 32);
;       *(u32x4*)(D + soff + s * 64 * LROW) = ra[s];
;       *(u32x4*)(D + T2 + soff + s * 64 * LROW) = rb[s];
;       ra[s] = *(const u32x4*)(an + s * astep + a_voff);
;       rb[s] = *(const u32x4*)(bn + s * bstep + b_voff);
; #pragma unroll
;       for (int mi = 0; mi < 4; ++mi)
; #pragma unroll
;         for (int ni = 0; ni < 2; ++ni) acc[mi][ni] = MFMA32(a[mi], b[ni], acc[mi][ni]);
;     }
;     __syncthreads();
;   }
	ds_read_b128 v[196:199], v194 offset:32768
	ds_read_b128 v[212:215], v160 offset:32768
	ds_read_b128 v[216:219], v160 offset:36864
	ds_read_b128 v[200:203], v194 offset:36864
	ds_read_b128 v[204:207], v194 offset:40960
	ds_read_b128 v[208:211], v194 offset:45056
	s_add_i32 s56, s56, 1
	s_waitcnt lgkmcnt(0)
	v_mfma_f32_32x32x16_bf16 v[114:129], v[196:199], v[212:215], v[114:129]
	ds_read_b128 v[220:223], v195 offset:32768
	ds_read_b128 v[242:245], v161 offset:32768
	v_mfma_f32_32x32x16_bf16 v[50:65], v[196:199], v[216:219], v[50:65]
	ds_read_b128 v[246:249], v161 offset:36864
	ds_read_b128 v[224:227], v195 offset:36864
	v_mfma_f32_32x32x16_bf16 v[98:113], v[200:203], v[212:215], v[98:113]
	ds_read_b128 v[228:231], v195 offset:40960
	ds_read_b128 v[238:241], v195 offset:45056
	v_mfma_f32_32x32x16_bf16 v[34:49], v[200:203], v[216:219], v[34:49]
	s_add_u32 m0, s58, 0x0
	s_nop 0
	global_load_lds_dwordx4 v164, s[52:53]
	v_mfma_f32_32x32x16_bf16 v[82:97], v[204:207], v[212:215], v[82:97]
	s_add_u32 m0, s58, 0x400
	s_nop 0
	global_load_lds_dwordx4 v165, s[52:53]
	v_mfma_f32_32x32x16_bf16 v[18:33], v[204:207], v[216:219], v[18:33]
	s_add_u32 m0, s58, 0x800
	s_nop 0
	global_load_lds_dwordx4 v130, s[52:53]
	v_mfma_f32_32x32x16_bf16 v[66:81], v[208:211], v[212:215], v[66:81]
	s_add_u32 m0, s58, 0xc00
	s_nop 0
	global_load_lds_dwordx4 v131, s[52:53]
	v_mfma_f32_32x32x16_bf16 v[2:17], v[208:211], v[216:219], v[2:17]
	s_waitcnt lgkmcnt(0)
	v_mfma_f32_32x32x16_bf16 v[114:129], v[220:223], v[242:245], v[114:129]
	ds_read_b128 v[196:199], v250 offset:32768
	ds_read_b128 v[212:215], v162 offset:32768
	v_mfma_f32_32x32x16_bf16 v[50:65], v[220:223], v[246:249], v[50:65]
	ds_read_b128 v[216:219], v162 offset:36864
	ds_read_b128 v[200:203], v250 offset:36864
	v_mfma_f32_32x32x16_bf16 v[98:113], v[224:227], v[242:245], v[98:113]
	ds_read_b128 v[204:207], v250 offset:40960
	ds_read_b128 v[208:211], v250 offset:45056
	v_mfma_f32_32x32x16_bf16 v[34:49], v[224:227], v[246:249], v[34:49]
	s_add_u32 m0, s59, 0x0
	s_nop 0
	global_load_lds_dwordx4 v164, s[54:55]
	v_mfma_f32_32x32x16_bf16 v[82:97], v[228:231], v[242:245], v[82:97]
	s_add_u32 m0, s59, 0x400
	s_nop 0
	global_load_lds_dwordx4 v165, s[54:55]
	v_mfma_f32_32x32x16_bf16 v[18:33], v[228:231], v[246:249], v[18:33]
	s_add_u32 m0, s59, 0x800
	s_nop 0
	global_load_lds_dwordx4 v130, s[54:55]
	v_mfma_f32_32x32x16_bf16 v[66:81], v[238:241], v[242:245], v[66:81]
	s_add_u32 m0, s59, 0xc00
	s_nop 0
	global_load_lds_dwordx4 v131, s[54:55]
	v_mfma_f32_32x32x16_bf16 v[2:17], v[238:241], v[246:249], v[2:17]
	s_waitcnt lgkmcnt(0)
	v_mfma_f32_32x32x16_bf16 v[114:129], v[196:199], v[212:215], v[114:129]
	ds_read_b128 v[220:223], v251 offset:32768
	ds_read_b128 v[242:245], v163 offset:32768
	v_mfma_f32_32x32x16_bf16 v[50:65], v[196:199], v[216:219], v[50:65]
	ds_read_b128 v[246:249], v163 offset:36864
	ds_read_b128 v[224:227], v251 offset:36864
	v_mfma_f32_32x32x16_bf16 v[98:113], v[200:203], v[212:215], v[98:113]
	ds_read_b128 v[228:231], v251 offset:40960
	ds_read_b128 v[238:241], v251 offset:45056
	v_mfma_f32_32x32x16_bf16 v[34:49], v[200:203], v[216:219], v[34:49]
	s_cmp_lt_u32 s56, s57
	s_cselect_b32 s60, 0x80, 0
	s_add_u32 s52, s52, s60
	s_addc_u32 s53, s53, 0
	s_add_u32 s54, s54, s60
	s_addc_u32 s55, s55, 0
	v_mfma_f32_32x32x16_bf16 v[82:97], v[204:207], v[212:215], v[82:97]
	v_mfma_f32_32x32x16_bf16 v[18:33], v[204:207], v[216:219], v[18:33]
	v_mfma_f32_32x32x16_bf16 v[66:81], v[208:211], v[212:215], v[66:81]
	v_mfma_f32_32x32x16_bf16 v[2:17], v[208:211], v[216:219], v[2:17]
	s_waitcnt lgkmcnt(0)
	v_mfma_f32_32x32x16_bf16 v[114:129], v[220:223], v[242:245], v[114:129]
	v_mfma_f32_32x32x16_bf16 v[50:65], v[220:223], v[246:249], v[50:65]
	v_mfma_f32_32x32x16_bf16 v[98:113], v[224:227], v[242:245], v[98:113]
	v_mfma_f32_32x32x16_bf16 v[34:49], v[224:227], v[246:249], v[34:49]
	v_mfma_f32_32x32x16_bf16 v[82:97], v[228:231], v[242:245], v[82:97]
	v_mfma_f32_32x32x16_bf16 v[18:33], v[228:231], v[246:249], v[18:33]
	v_mfma_f32_32x32x16_bf16 v[66:81], v[238:241], v[242:245], v[66:81]
	v_mfma_f32_32x32x16_bf16 v[2:17], v[238:241], v[246:249], v[2:17]
	s_waitcnt vmcnt(0)
	s_barrier
	ds_read_b128 v[196:199], v194 offset:0
	ds_read_b128 v[212:215], v160 offset:0
	ds_read_b128 v[216:219], v160 offset:4096
	ds_read_b128 v[200:203], v194 offset:4096
	ds_read_b128 v[204:207], v194 offset:8192
	ds_read_b128 v[208:211], v194 offset:12288
	s_cmp_lt_u32 s56, s57
	s_cbranch_scc1 .Lg_inproj_loop
	s_waitcnt lgkmcnt(0)
	s_nop 7
	s_nop 7
	s_branch .LBB0_195

; DI int tid512() { int t = threadIdx.x; asm volatile("" : "+v"(t)); return t; }
; #define A_LOAD(KB) { _Pragma("unroll") for (int i = 0; i < 2; ++i) { rk[i] = *(const u32x4*)(kp + (size_t)((KB) * 64 + 32 * i) * 1024); rv[i] = *(const u32x4*)(vp + (size_t)(64 * i) * TOK + (KB) * 64); } }
; #define A_STORE(STG) { char* D_ = smem + (STG) * ST; _Pragma("unroll") for (int i = 0; i < 2; ++i) { *(u32x4*)(D_ + ksoff + i * 32 * 272) = rk[i]; \
;       u32x2 lo2_ = {rv[i].x, rv[i].y}, hi2_ = {rv[i].z, rv[i].w}; *(u32x2*)(D_ + vsoff + i * 64 * VROW) = lo2_; *(u32x2*)(D_ + vsoff + i * 64 * VROW + 16) = hi2_; } }
; DI void attn_block(const Params& p, int layer, int hd, int q0, int nkeys, char* smem) {
;   constexpr int KT = 64 * 272, VROW = 144, ST = KT + 128 * VROW;
;   const int t = tid512(), lane = t & 63, w = t >> 6, mp = w >> 2, wq = w & 3, r = lane & 31, h = lane >> 5;
;   const bf16_t* DQ = (const bf16_t*)(p.ws + O_DQ);
;   const bf16_t* DK = (const bf16_t*)(p.ws + O_DK);
;   const bf16_t* DVT = (const bf16_t*)(p.ws + O_DVT);
;   const float* scal = (const float*)(p.ws + O_SCAL);
;   const int q = q0 + 32 * wq + r;
;   bf16x8 qf[4];
; #pragma unroll
;   for (int s = 0; s < 4; ++s) qf[s] = *(const bf16x8*)(DQ + (size_t)q * 1024 + hd * 128 + 64 * mp + 16 * s + 8 * h);
;   const int nkb = nkeys >> 6, lastkb = nkb - 1;
;   const bf16_t* kp = DK + (size_t)(t >> 4) * 1024 + hd * 128 + (t & 15) * 8;
;   const int ksoff = (t >> 4) * 272 + (t & 15) * 16;
;   const bf16_t* vp = DVT + (size_t)(hd * 128 + (t >> 3)) * TOK + (t & 7) * 8;
;   const int vsoff = KT + (t >> 3) * VROW + ((t & 7) >> 1) * 32 + (t & 1) * 8;
;   u32x4 rk[2], rv[2];
;     ...
;   A_LOAD(0);
;   __syncthreads();
;   A_STORE(0);
;   A_LOAD(lastkb < 1 ? lastkb : 1);
;   A_STORE(1);
;   A_LOAD(lastkb < 2 ? lastkb : 2);
;   __syncthreads();
;   float m = -1e30f, l = 0.f;
;   f32x16 o[4];
; #pragma unroll
;   for (int vt = 0; vt < 4; ++vt)
; #pragma unroll
;     for (int i = 0; i < 16; ++i) o[vt][i] = 0.f;
;   f32x16 sc[2], sn[2];
;   A_SCORES(sc, 0);
.LBB0_392:
	s_lshl_b32 s4, s6, 7
	v_mov_b32_e32 v202, v0
	s_and_b32 s4, s4, 0x1f80
	s_addk_i32 s4, 0x100
	v_lshrrev_b32_e32 v2, 1, v202
	v_and_b32_e32 v200, 31, v202
	v_and_b32_e32 v201, 0x60, v2
	v_or3_b32 v198, v200, s4, v201
	v_readlane_b32 s4, v254, 9
	v_lshlrev_b32_e32 v180, 11, v198
	v_readlane_b32 s5, v254, 10
	v_ashrrev_i32_e32 v199, 8, v202
	v_lshlrev_b32_e32 v4, 6, v199
	v_lshl_add_u64 v[2:3], s[4:5], 0, v[180:181]
	s_lshl_b32 s4, s6, 1
	s_and_b32 s94, s4, 0x7fffff80
	s_lshl_b32 s22, s94, 1
	v_bfe_u32 v193, v202, 5, 1
	v_lshl_add_u64 v[2:3], v[2:3], 0, s[22:23]
	v_ashrrev_i32_e32 v5, 31, v4
	v_lshl_add_u64 v[2:3], v[4:5], 1, v[2:3]
	v_lshlrev_b32_e32 v180, 4, v193
	v_ashrrev_i32_e32 v34, 4, v202
	v_lshl_add_u64 v[2:3], v[2:3], 0, v[180:181]
	v_ashrrev_i32_e32 v35, 31, v34
	v_readlane_b32 s4, v254, 11
	global_load_dwordx4 v[130:133], v[2:3], off
	global_load_dwordx4 v[134:137], v[2:3], off offset:32
	global_load_dwordx4 v[138:141], v[2:3], off offset:64
	global_load_dwordx4 v[142:145], v[2:3], off offset:96
	v_lshlrev_b64 v[2:3], 11, v[34:35]
	v_readlane_b32 s5, v254, 12
	v_lshlrev_b32_e32 v35, 4, v202
	v_and_b32_e32 v36, 0xf0, v35
	v_lshl_add_u64 v[2:3], s[4:5], 0, v[2:3]
	v_lshl_add_u64 v[2:3], v[2:3], 0, s[22:23]
	v_mov_b32_e32 v37, v181
	v_readlane_b32 s4, v253, 54
	v_lshl_add_u64 v[162:163], v[2:3], 0, v[36:37]
	v_ashrrev_i32_e32 v37, 3, v202
	v_readlane_b32 s5, v253, 55
	v_add_u32_e32 v4, s94, v37
	v_mov_b32_e32 v5, v181
	v_mov_b64_e32 v[2:3], s[4:5]
	v_mad_i64_i32 v[2:3], s[4:5], v4, s29, v[2:3]
	v_and_b32_e32 v4, 7, v202
	v_lshlrev_b32_e32 v4, 4, v4
	v_add_co_u32_e32 v10, vcc, s46, v162
	v_lshl_add_u64 v[164:165], v[2:3], 0, v[4:5]
	s_nop 0
	v_addc_co_u32_e32 v11, vcc, 0, v163, vcc
	v_add_co_u32_e32 v38, vcc, s30, v164
	global_load_dwordx4 v[2:5], v[162:163], off
	global_load_dwordx4 v[6:9], v[164:165], off
	v_addc_co_u32_e32 v39, vcc, 0, v165, vcc
	v_add_co_u32_e32 v18, vcc, s87, v162
	global_load_dwordx4 v[10:13], v[10:11], off
	s_nop 0
	global_load_dwordx4 v[14:17], v[38:39], off
	v_addc_co_u32_e32 v19, vcc, 0, v163, vcc
	v_add_co_u32_e32 v26, vcc, s47, v162
	s_waitcnt vmcnt(63) expcnt(7) lgkmcnt(15)
	s_barrier
	global_load_dwordx4 v[18:21], v[18:19], off
	s_nop 0
	global_load_dwordx4 v[22:25], v[164:165], off offset:128
	v_addc_co_u32_e32 v27, vcc, 0, v163, vcc
	global_load_dwordx4 v[26:29], v[26:27], off
	s_nop 0
	global_load_dwordx4 v[30:33], v[38:39], off offset:128
	v_lshlrev_b32_e32 v40, 3, v202
	v_mul_lo_u32 v37, v37, s28
	s_movk_i32 s4, 0x110
	v_and_b32_e32 v35, 0x60, v35
	v_mad_u64_u32 v[194:195], s[4:5], v34, s4, v[36:37]
	v_and_or_b32 v34, v40, 8, v37
	v_add_u32_e32 v205, v34, v35
	v_add_u32_e32 v36, 16, v194
	v_add_u32_e32 v34, 16, v205
	v_add_u32_e32 v35, 0x4000, v34
	v_add_u32_e32 v37, 0x6800, v34
	v_add_u32_e32 v40, 0xd000, v34
	global_load_dwordx4 v[146:149], v[164:165], off offset:256
	s_mov_b32 s4, 0x50000
	s_mov_b32 s42, 1
	v_mul_u32_u24_e32 v203, 0x90, v200
	v_mov_b32_e32 v204, 0xf149f2ca
	v_mov_b32_e32 v195, 0
	s_waitcnt vmcnt(0)
	ds_write_b128 v36, v[2:5]
	ds_write2_b64 v35, v[6:7], v[8:9] offset0:128 offset1:130
	ds_write_b128 v36, v[10:13] offset:8704
	ds_write2_b64 v37, v[14:15], v[16:17] offset1:2
	ds_write_b128 v36, v[18:21] offset:35840
	ds_write2_b64 v40, v[22:23], v[24:25] offset1:2
	ds_write_b128 v36, v[26:29] offset:44544
	v_add_u32_e32 v2, 0xf000, v34
	ds_write2_b64 v2, v[30:31], v[32:33] offset0:128 offset1:130
	v_add_co_u32_e32 v2, vcc, s84, v162
	global_load_dwordx4 v[150:153], v[38:39], off offset:256
	s_nop 0
	v_addc_co_u32_e32 v3, vcc, 0, v163, vcc
	v_add_co_u32_e32 v4, vcc, s4, v162
	s_mov_b32 s4, 0
	s_nop 0
	v_addc_co_u32_e32 v5, vcc, 0, v163, vcc
	global_load_dwordx4 v[158:161], v[2:3], off
	global_load_dwordx4 v[154:157], v[4:5], off
	v_lshl_add_u32 v2, v199, 7, 16
	v_mul_u32_u24_e32 v3, 0x110, v200
	v_add3_u32 v206, v2, v180, v3
	s_waitcnt lgkmcnt(0)
	s_barrier
	ds_read_b128 v[2:5], v206
	ds_read_b128 v[6:9], v206 offset:32
	s_waitcnt lgkmcnt(1)
	v_mfma_f32_32x32x16_bf16 v[114:129], v[2:5], v[130:133], 0
	s_mov_b32 s18, s4
	s_mov_b32 s19, s4
	s_mov_b32 s5, s4
	s_mov_b32 s6, s4
	s_mov_b32 s7, s4
	s_mov_b32 s8, s4
	s_mov_b32 s9, s4
	s_waitcnt lgkmcnt(0)
	v_mfma_f32_32x32x16_bf16 v[114:129], v[6:9], v[134:137], v[114:129]
	ds_read_b128 v[2:5], v206 offset:64
	ds_read_b128 v[6:9], v206 offset:96
	s_mov_b32 s10, s4
	s_mov_b32 s11, s4
	s_mov_b32 s12, s4
	s_mov_b32 s13, s4
	s_mov_b32 s14, s4
	s_mov_b32 s15, s4
	s_waitcnt lgkmcnt(1)
	v_mfma_f32_32x32x16_bf16 v[114:129], v[2:5], v[138:141], v[114:129]
	ds_read_b128 v[2:5], v206 offset:8704
	ds_read_b128 v[10:13], v206 offset:8736
	s_mov_b32 s16, s4
	s_mov_b32 s17, s4
	v_mov_b64_e32 v[64:65], s[18:19]
	v_mov_b64_e32 v[50:51], s[4:5]
	v_mov_b64_e32 v[62:63], s[16:17]
	v_mov_b64_e32 v[60:61], s[14:15]
	s_waitcnt lgkmcnt(1)
	v_mfma_f32_32x32x16_bf16 v[98:113], v[2:5], v[130:133], 0
	ds_read_b128 v[2:5], v206 offset:8768
	v_mov_b64_e32 v[58:59], s[12:13]
	v_mov_b64_e32 v[56:57], s[10:11]
	v_mov_b64_e32 v[54:55], s[8:9]
	v_mov_b64_e32 v[52:53], s[6:7]
	v_mov_b64_e32 v[18:19], v[50:51]
	v_mov_b64_e32 v[34:35], v[50:51]
	s_waitcnt lgkmcnt(1)
	v_mfma_f32_32x32x16_bf16 v[98:113], v[10:13], v[134:137], v[98:113]
	s_mov_b32 s5, 2
	v_mov_b64_e32 v[20:21], v[52:53]
	v_mov_b64_e32 v[22:23], v[54:55]
	v_mov_b64_e32 v[24:25], v[56:57]
	v_mov_b64_e32 v[26:27], v[58:59]
	v_mov_b64_e32 v[28:29], v[60:61]
	v_mov_b64_e32 v[30:31], v[62:63]
	v_mfma_f32_32x32x16_bf16 v[114:129], v[6:9], v[142:145], v[114:129]
	ds_read_b128 v[6:9], v206 offset:8800
	v_mov_b64_e32 v[32:33], v[64:65]
	v_mov_b64_e32 v[36:37], v[52:53]
	v_mov_b64_e32 v[38:39], v[54:55]
	v_mov_b64_e32 v[40:41], v[56:57]
	v_mov_b64_e32 v[42:43], v[58:59]
	v_mov_b64_e32 v[44:45], v[60:61]
	s_waitcnt lgkmcnt(1)
; DI float ex2(float x) { return __builtin_amdgcn_exp2f(x); }
; #define A_LOAD(KB) { _Pragma("unroll") for (int i = 0; i < 2; ++i) { rk[i] = *(const u32x4*)(kp + (size_t)((KB) * 64 + 32 * i) * 1024); rv[i] = *(const u32x4*)(vp + (size_t)(64 * i) * TOK + (KB) * 64); } }
; #define A_STORE(STG) { char* D_ = smem + (STG) * ST; _Pragma("unroll") for (int i = 0; i < 2; ++i) { *(u32x4*)(D_ + ksoff + i * 32 * 272) = rk[i]; \
;       u32x2 lo2_ = {rv[i].x, rv[i].y}, hi2_ = {rv[i].z, rv[i].w}; *(u32x2*)(D_ + vsoff + i * 64 * VROW) = lo2_; *(u32x2*)(D_ + vsoff + i * 64 * VROW + 16) = hi2_; } }
; #define A_SCORES(DST, STG) { const char* Ks_ = smem + (STG) * ST; _Pragma("unroll") for (int kt = 0; kt < 2; ++kt) { \
;       _Pragma("unroll") for (int i = 0; i < 16; ++i) DST[kt][i] = 0.f; \
;       _Pragma("unroll") for (int s = 0; s < 4; ++s) { const bf16x8 a_ = *(const bf16x8*)(Ks_ + (32 * kt + r) * 272 + 128 * mp + 32 * s + 16 * h); DST[kt] = MFMA32(a_, qf[s], DST[kt]); } } }
; DI void attn_block(const Params& p, int layer, int hd, int q0, int nkeys, char* smem) {
;     ...
;   float m = -1e30f, l = 0.f;
;   f32x16 o[4];
; #pragma unroll
;   for (int vt = 0; vt < 4; ++vt)
; #pragma unroll
;     for (int i = 0; i < 16; ++i) o[vt][i] = 0.f;
;   f32x16 sc[2], sn[2];
;   A_SCORES(sc, 0);
;   int c0 = 0, c1 = 1, c2 = 2;
;   for (int kb = 0; kb < nkb; ++kb) {
;     const char* Vs = smem + c0 * ST + KT;
;     A_STORE(c2);
;     A_LOAD((kb + 3 < lastkb) ? kb + 3 : lastkb);
;     if (kb + 1 < nkb) A_SCORES(sn, c1);
;     float mx = fmaxf(sc[0][0], sc[1][0]);
; #pragma unroll
;     for (int i = 1; i < 16; ++i) mx = fmaxf(mx, fmaxf(sc[0][i], sc[1][i]));
;     {
;       const auto pr_ = __builtin_amdgcn_permlane32_swap(__float_as_uint(mx), __float_as_uint(mx), false, false);
;       mx = fmaxf(__uint_as_float(pr_[0]), __uint_as_float(pr_[1]));
;     }
;     if (__any(mx > m + 8.f)) {
;       const float mn = (mx > m + 8.f) ? mx : m;
;       const float alpha = ex2(m - mn);
;       l *= alpha;
; #pragma unroll
;       for (int vt = 0; vt < 4; ++vt)
; #pragma unroll
;         for (int i = 0; i < 16; ++i) o[vt][i] *= alpha;
;       m = mn;
;     }
;     bf16x8 va[2][4];
;     const char* vbase = Vs + r * VROW + 16 * h;
; #pragma unroll
;     for (int vt = 0; vt < 4; ++vt) va[0][vt] = *(const bf16x8*)(vbase + 32 * vt * VROW);
	v_mfma_f32_32x32x16_bf16 v[98:113], v[2:5], v[138:141], v[98:113]
	v_mov_b64_e32 v[46:47], v[62:63]
	v_mov_b64_e32 v[48:49], v[64:65]
	s_waitcnt lgkmcnt(0)
	v_mfma_f32_32x32x16_bf16 v[98:113], v[6:9], v[142:145], v[98:113]
	v_mov_b64_e32 v[2:3], v[50:51]
	v_mov_b64_e32 v[4:5], v[52:53]
	v_mov_b64_e32 v[6:7], v[54:55]
	v_mov_b64_e32 v[8:9], v[56:57]
	v_mov_b64_e32 v[10:11], v[58:59]
	v_mov_b64_e32 v[12:13], v[60:61]
	v_mov_b64_e32 v[14:15], v[62:63]
	v_mov_b64_e32 v[16:17], v[64:65]
	v_mov_b32_e32 v196, 0x1a410
	v_lshl_add_u32 v196, v0, 2, v196
	ds_write_b32 v196, v170 offset:0
	ds_write_b32 v196, v171 offset:2048
	ds_write_b32 v196, v172 offset:4096
	ds_write_b32 v196, v173 offset:6144
	ds_write_b32 v196, v174 offset:8192
	ds_write_b32 v196, v175 offset:10240
	ds_write_b32 v196, v176 offset:12288
	ds_write_b32 v196, v177 offset:14336
	v_readfirstlane_b32 s52, v162
	v_readfirstlane_b32 s53, v163
	v_readfirstlane_b32 s56, v164
	v_readfirstlane_b32 s57, v165
	s_nop 3
	s_add_u32 s54, s52, s46
	s_addc_u32 s55, s53, 0
	s_add_u32 s58, s56, s30
	s_addc_u32 s59, s57, 0
	v_subrev_u32_e32 v175, s52, v162
	v_subrev_u32_e32 v176, s56, v164
	v_add_u32_e32 v162, 0x11800, v206
	v_add3_u32 v163, v203, v180, 16
	v_add_u32_e32 v174, 0x11810, v205
	v_add_u32_e32 v165, 0x11810, v194
	v_add_u32_e32 v164, 0xd000, v163
	s_mov_b32 s6, 0
	s_nop 7
	v_max3_f32 v246, v114, v115, v116
	v_max3_f32 v247, v117, v118, v119
	v_max3_f32 v246, v246, v120, v121
	v_max3_f32 v247, v247, v122, v123
	v_max3_f32 v246, v246, v124, v125
	v_max3_f32 v247, v247, v126, v127
	v_max3_f32 v246, v246, v128, v129
	v_max3_f32 v247, v247, v98, v99
	v_max3_f32 v246, v246, v100, v101
	v_max3_f32 v247, v247, v102, v103
	v_max3_f32 v246, v246, v104, v105
	v_max3_f32 v247, v247, v106, v107
	v_max3_f32 v246, v246, v108, v109
	v_max3_f32 v247, v247, v110, v111
	v_max3_f32 v246, v246, v112, v113
	v_max_f32_e32 v246, v246, v247
	v_mov_b32_e32 v247, v246
	s_nop 1
	v_permlane32_swap_b32_e32 v246, v247
	v_max_f32_e32 v246, v246, v247
	v_sub_f32_e32 v114, v114, v246
	v_sub_f32_e32 v115, v115, v246
	v_sub_f32_e32 v116, v116, v246
	v_sub_f32_e32 v117, v117, v246
	v_sub_f32_e32 v118, v118, v246
	v_sub_f32_e32 v119, v119, v246
	v_sub_f32_e32 v120, v120, v246
	v_sub_f32_e32 v121, v121, v246
	v_sub_f32_e32 v122, v122, v246
	v_sub_f32_e32 v123, v123, v246
	v_sub_f32_e32 v124, v124, v246
	v_sub_f32_e32 v125, v125, v246
	v_sub_f32_e32 v126, v126, v246
	v_sub_f32_e32 v127, v127, v246
	v_sub_f32_e32 v128, v128, v246
	v_sub_f32_e32 v129, v129, v246
	v_sub_f32_e32 v98, v98, v246
	v_sub_f32_e32 v99, v99, v246
	v_sub_f32_e32 v100, v100, v246
	v_sub_f32_e32 v101, v101, v246
	v_sub_f32_e32 v102, v102, v246
	v_sub_f32_e32 v103, v103, v246
	v_sub_f32_e32 v104, v104, v246
	v_sub_f32_e32 v105, v105, v246
	v_sub_f32_e32 v106, v106, v246
	v_sub_f32_e32 v107, v107, v246
	v_sub_f32_e32 v108, v108, v246
	v_sub_f32_e32 v109, v109, v246
	v_sub_f32_e32 v110, v110, v246
	v_sub_f32_e32 v111, v111, v246
	v_sub_f32_e32 v112, v112, v246
	v_sub_f32_e32 v113, v113, v246
	v_mul_f32_e32 v66, -1.0, v246
	v_mov_b32_e32 v197, 0
	v_mov_b32_e32 v207, 0
	v_mov_b32_e32 v67, v66
	v_mov_b32_e32 v68, v66
	v_mov_b32_e32 v69, v66
	v_mov_b32_e32 v70, v66
	v_mov_b32_e32 v71, v66
	v_mov_b32_e32 v72, v66
	v_mov_b32_e32 v73, v66
	v_mov_b32_e32 v74, v66
	v_mov_b32_e32 v75, v66
	v_mov_b32_e32 v76, v66
	v_mov_b32_e32 v77, v66
	v_mov_b32_e32 v78, v66
	v_mov_b32_e32 v79, v66
	v_mov_b32_e32 v80, v66
	v_mov_b32_e32 v81, v66
	s_waitcnt vmcnt(0)
	s_waitcnt lgkmcnt(0)
	ds_read_b128 v[220:223], v163 offset:17408
	ds_read_b128 v[208:211], v206 offset:35840
	ds_read_b128 v[224:227], v163 offset:22016
	ds_read_b128 v[212:215], v206 offset:35872
	ds_read_b128 v[228:231], v163 offset:26624
	ds_read_b128 v[216:219], v206 offset:35904
	ds_read_b128 v[238:241], v163 offset:31232
; #define MFMA32(a, b, c) __builtin_amdgcn_mfma_f32_32x32x16_bf16((a), (b), (c), 0, 0, 0)
; DI float ex2(float x) { return __builtin_amdgcn_exp2f(x); }
; #define A_LOAD(KB) { _Pragma("unroll") for (int i = 0; i < 2; ++i) { rk[i] = *(const u32x4*)(kp + (size_t)((KB) * 64 + 32 * i) * 1024); rv[i] = *(const u32x4*)(vp + (size_t)(64 * i) * TOK + (KB) * 64); } }
; DI void attn_block(const Params& p, int layer, int hd, int q0, int nkeys, char* smem) {
;     ...
;   for (int kb = 0; kb < nkb; ++kb) {
;     const char* Vs = smem + c0 * ST + KT;
;     A_STORE(c2);
;     A_LOAD((kb + 3 < lastkb) ? kb + 3 : lastkb);
;     if (kb + 1 < nkb) A_SCORES(sn, c1);
;     float mx = fmaxf(sc[0][0], sc[1][0]);
; #pragma unroll
;     for (int i = 1; i < 16; ++i) mx = fmaxf(mx, fmaxf(sc[0][i], sc[1][i]));
;     {
;       const auto pr_ = __builtin_amdgcn_permlane32_swap(__float_as_uint(mx), __float_as_uint(mx), false, false);
;       mx = fmaxf(__uint_as_float(pr_[0]), __uint_as_float(pr_[1]));
;     }
;     if (__any(mx > m + 8.f)) {
;       const float mn = (mx > m + 8.f) ? mx : m;
;       const float alpha = ex2(m - mn);
;       l *= alpha;
; #pragma unroll
;       for (int vt = 0; vt < 4; ++vt)
; #pragma unroll
;         for (int i = 0; i < 16; ++i) o[vt][i] *= alpha;
;       m = mn;
;     }
;     bf16x8 va[2][4];
;     const char* vbase = Vs + r * VROW + 16 * h;
; #pragma unroll
;     for (int vt = 0; vt < 4; ++vt) va[0][vt] = *(const bf16x8*)(vbase + 32 * vt * VROW);
;     float ls[4] = {0.f, 0.f, 0.f, 0.f};
; #pragma unroll
;     for (int st = 0; st < 4; ++st) {
;       if (st < 3) {
; #pragma unroll
;         for (int vt = 0; vt < 4; ++vt) va[(st + 1) & 1][vt] = *(const bf16x8*)(vbase + 32 * vt * VROW + (st + 1) * 32);
;       }
;       float pv[8];
; #pragma unroll
;       for (int i = 0; i < 8; ++i) { pv[i] = ex2(sc[st >> 1][8 * (st & 1) + i] - m); ls[i & 3] += pv[i]; }
;       u32x4 pk; pk.x = pack2(pv[0], pv[1]); pk.y = pack2(pv[2], pv[3]); pk.z = pack2(pv[4], pv[5]); pk.w = pack2(pv[6], pv[7]);
;       const bf16x8 pb = __builtin_bit_cast(bf16x8, pk);
; #pragma unroll
;       for (int vt = 0; vt < 4; ++vt) o[vt] = MFMA32(va[st & 1][vt], pb, o[vt]);
;     }
;     l += (ls[0] + ls[1]) + (ls[2] + ls[3]);
;     __syncthreads();
;     sc[0] = sn[0]; sc[1] = sn[1];
;     { const int tmp = c0; c0 = c1; c1 = c2; c2 = tmp; }
.Lat_top_0:
	s_waitcnt lgkmcnt(5)
	v_mfma_f32_32x32x16_bf16 v[82:97], v[208:211], v[130:133], v[66:81]
	ds_read_b128 v[208:211], v206 offset:35936
	s_min_i32 s60, s6, 0x80
	s_add_i32 s60, s60, 3
	v_exp_f32_e32 v246, v114
	v_exp_f32_e32 v247, v115
	v_exp_f32_e32 v248, v116
	v_exp_f32_e32 v249, v117
	v_add_f32_e32 v197, v197, v246
	s_waitcnt lgkmcnt(4)
	v_mfma_f32_32x32x16_bf16 v[82:97], v[212:215], v[134:137], v[82:97]
	s_waitcnt vmcnt(3)
	ds_write_b128 v165, v[158:161] offset:0
	v_lshl_add_u32 v177, s60, 17, v175
	global_load_dwordx4 v[158:161], v177, s[52:53]
	v_add_f32_e32 v207, v207, v247
	v_cvt_pk_bf16_f32 v242, v246, v247
	v_exp_f32_e32 v250, v118
	v_add_f32_e32 v197, v197, v248
	v_add_f32_e32 v207, v207, v249
	s_waitcnt lgkmcnt(3)
	v_mfma_f32_32x32x16_bf16 v[82:97], v[216:219], v[138:141], v[82:97]
	v_cvt_pk_bf16_f32 v243, v248, v249
	v_exp_f32_e32 v251, v119
	v_exp_f32_e32 v237, v120
	v_add_f32_e32 v197, v197, v250
	v_exp_f32_e32 v196, v121
	s_waitcnt lgkmcnt(1)
	v_mfma_f32_32x32x16_bf16 v[82:97], v[208:211], v[142:145], v[82:97]
	v_add_f32_e32 v207, v207, v251
	v_cvt_pk_bf16_f32 v244, v250, v251
	v_cvt_pk_bf16_f32 v245, v237, v196
	v_add_f32_e32 v197, v197, v237
	v_add_f32_e32 v207, v207, v196
	v_mfma_f32_32x32x16_bf16 v[34:49], v[220:223], v[242:245], v[34:49]
	ds_read_b128 v[220:223], v163 offset:17440
	v_exp_f32_e32 v246, v122
	v_exp_f32_e32 v247, v123
	v_exp_f32_e32 v248, v124
	v_exp_f32_e32 v249, v125
	v_add_f32_e32 v197, v197, v246
	v_mfma_f32_32x32x16_bf16 v[18:33], v[224:227], v[242:245], v[18:33]
	ds_read_b128 v[224:227], v163 offset:22048
	s_waitcnt vmcnt(3)
	ds_write_b128 v165, v[154:157] offset:8704
	global_load_dwordx4 v[154:157], v177, s[54:55]
	v_add_f32_e32 v207, v207, v247
	v_cvt_pk_bf16_f32 v170, v246, v247
	v_exp_f32_e32 v250, v126
	v_add_f32_e32 v197, v197, v248
	v_add_f32_e32 v207, v207, v249
	v_mfma_f32_32x32x16_bf16 v[2:17], v[228:231], v[242:245], v[2:17]
	ds_read_b128 v[228:231], v163 offset:26656
	v_cvt_pk_bf16_f32 v171, v248, v249
	v_exp_f32_e32 v251, v127
	v_exp_f32_e32 v237, v128
	v_add_f32_e32 v197, v197, v250
	v_exp_f32_e32 v196, v129
	v_mfma_f32_32x32x16_bf16 v[50:65], v[238:241], v[242:245], v[50:65]
	ds_read_b128 v[238:241], v163 offset:31264
	v_add_f32_e32 v207, v207, v251
	v_cvt_pk_bf16_f32 v172, v250, v251
	v_cvt_pk_bf16_f32 v173, v237, v196
	v_add_f32_e32 v197, v197, v237
	v_add_f32_e32 v207, v207, v196
	s_waitcnt lgkmcnt(4)
	v_mfma_f32_32x32x16_bf16 v[34:49], v[220:223], v[170:173], v[34:49]
	ds_read_b128 v[220:223], v163 offset:17472
	v_exp_f32_e32 v246, v98
	v_exp_f32_e32 v247, v99
	v_exp_f32_e32 v248, v100
	v_exp_f32_e32 v249, v101
	v_add_f32_e32 v197, v197, v246
	s_waitcnt lgkmcnt(4)
	v_mfma_f32_32x32x16_bf16 v[18:33], v[224:227], v[170:173], v[18:33]
	ds_read_b128 v[224:227], v163 offset:22080
	s_waitcnt vmcnt(3)
	ds_write_b64 v174, v[146:147] offset:17408
	ds_write_b64 v174, v[148:149] offset:17424
	v_lshl_add_u32 v177, s60, 7, v176
	global_load_dwordx4 v[146:149], v177, s[56:57]
	v_add_f32_e32 v207, v207, v247
	v_cvt_pk_bf16_f32 v242, v246, v247
	v_exp_f32_e32 v250, v102
	v_add_f32_e32 v197, v197, v248
	v_add_f32_e32 v207, v207, v249
	s_waitcnt lgkmcnt(5)
	v_mfma_f32_32x32x16_bf16 v[2:17], v[228:231], v[170:173], v[2:17]
	ds_read_b128 v[228:231], v163 offset:26688
	v_cvt_pk_bf16_f32 v243, v248, v249
	v_exp_f32_e32 v251, v103
	v_exp_f32_e32 v237, v104
	v_add_f32_e32 v197, v197, v250
	v_exp_f32_e32 v196, v105
	s_waitcnt lgkmcnt(5)
	v_mfma_f32_32x32x16_bf16 v[50:65], v[238:241], v[170:173], v[50:65]
	ds_read_b128 v[238:241], v163 offset:31296
	v_add_f32_e32 v207, v207, v251
	v_cvt_pk_bf16_f32 v244, v250, v251
	v_cvt_pk_bf16_f32 v245, v237, v196
	v_add_f32_e32 v197, v197, v237
	v_add_f32_e32 v207, v207, v196
	s_waitcnt lgkmcnt(5)
	v_mfma_f32_32x32x16_bf16 v[34:49], v[220:223], v[242:245], v[34:49]
	ds_read_b128 v[220:223], v163 offset:17504
	ds_read_b128 v[212:215], v206 offset:44544
	v_exp_f32_e32 v246, v106
	v_exp_f32_e32 v247, v107
	v_exp_f32_e32 v248, v108
	v_exp_f32_e32 v249, v109
	v_add_f32_e32 v197, v197, v246
	s_waitcnt lgkmcnt(6)
	v_mfma_f32_32x32x16_bf16 v[18:33], v[224:227], v[242:245], v[18:33]
	ds_read_b128 v[224:227], v163 offset:22112
	s_waitcnt vmcnt(3)
	ds_write_b64 v174, v[150:151] offset:26624
	ds_write_b64 v174, v[152:153] offset:26640
	global_load_dwordx4 v[150:153], v177, s[58:59]
	ds_read_b128 v[216:219], v206 offset:44576
	v_add_f32_e32 v207, v207, v247
	v_cvt_pk_bf16_f32 v170, v246, v247
	v_exp_f32_e32 v250, v110
	v_add_f32_e32 v197, v197, v248
	v_add_f32_e32 v207, v207, v249
	s_waitcnt lgkmcnt(7)
	v_mfma_f32_32x32x16_bf16 v[2:17], v[228:231], v[242:245], v[2:17]
	ds_read_b128 v[228:231], v163 offset:26720
	ds_read_b128 v[208:211], v206 offset:44608
	v_cvt_pk_bf16_f32 v171, v248, v249
	v_exp_f32_e32 v251, v111
	v_exp_f32_e32 v237, v112
	v_add_f32_e32 v197, v197, v250
	v_exp_f32_e32 v196, v113
	s_waitcnt lgkmcnt(8)
	v_mfma_f32_32x32x16_bf16 v[50:65], v[238:241], v[242:245], v[50:65]
	ds_read_b128 v[238:241], v163 offset:31328
	v_add_f32_e32 v207, v207, v251
	v_cvt_pk_bf16_f32 v172, v250, v251
	v_cvt_pk_bf16_f32 v173, v237, v196
	v_add_f32_e32 v197, v197, v237
	v_add_f32_e32 v207, v207, v196
	s_waitcnt lgkmcnt(7)
	v_mfma_f32_32x32x16_bf16 v[114:129], v[212:215], v[130:133], v[66:81]
	ds_read_b128 v[212:215], v206 offset:44640
	v_max3_f32 v246, v82, v83, v84
	s_waitcnt lgkmcnt(4)
	v_mfma_f32_32x32x16_bf16 v[114:129], v[216:219], v[134:137], v[114:129]
	v_max3_f32 v247, v85, v86, v87
	s_waitcnt lgkmcnt(2)
	v_mfma_f32_32x32x16_bf16 v[114:129], v[208:211], v[138:141], v[114:129]
	v_max3_f32 v246, v246, v88, v89
	s_waitcnt lgkmcnt(0)
	v_mfma_f32_32x32x16_bf16 v[114:129], v[212:215], v[142:145], v[114:129]
	v_max3_f32 v247, v247, v90, v91
	s_waitcnt lgkmcnt(0)
	s_barrier
	v_mfma_f32_32x32x16_bf16 v[34:49], v[220:223], v[170:173], v[34:49]
	ds_read_b128 v[220:223], v164 offset:0
	ds_read_b128 v[208:211], v162 offset:0
	v_max3_f32 v246, v246, v92, v93
	v_max3_f32 v247, v247, v94, v95
	v_mfma_f32_32x32x16_bf16 v[18:33], v[224:227], v[170:173], v[18:33]
	ds_read_b128 v[224:227], v164 offset:4608
	ds_read_b128 v[212:215], v162 offset:32
	v_max3_f32 v246, v246, v96, v97
	v_mfma_f32_32x32x16_bf16 v[2:17], v[228:231], v[170:173], v[2:17]
	ds_read_b128 v[228:231], v164 offset:9216
	ds_read_b128 v[216:219], v162 offset:64
	v_max3_f32 v247, v247, v114, v115
	v_max3_f32 v246, v246, v116, v117
	v_max3_f32 v247, v247, v118, v119
	v_max3_f32 v246, v246, v120, v121
	v_mfma_f32_32x32x16_bf16 v[50:65], v[238:241], v[170:173], v[50:65]
	ds_read_b128 v[238:241], v164 offset:13824
	v_max3_f32 v247, v247, v122, v123
	v_max3_f32 v246, v246, v124, v125
	v_max3_f32 v247, v247, v126, v127
	v_max3_f32 v246, v246, v128, v129
	v_max_f32_e32 v246, v246, v247
	v_mov_b32_e32 v247, v246
	s_nop 1
	v_permlane32_swap_b32_e32 v246, v247
	v_max_f32_e32 v246, v246, v247
	v_cmp_lt_f32_e32 vcc, 0x41000000, v246
	s_cbranch_vccnz .Lat_rare_0

; #define MFMA32(a, b, c) __builtin_amdgcn_mfma_f32_32x32x16_bf16((a), (b), (c), 0, 0, 0)
; DI float ex2(float x) { return __builtin_amdgcn_exp2f(x); }
; #define A_LOAD(KB) { _Pragma("unroll") for (int i = 0; i < 2; ++i) { rk[i] = *(const u32x4*)(kp + (size_t)((KB) * 64 + 32 * i) * 1024); rv[i] = *(const u32x4*)(vp + (size_t)(64 * i) * TOK + (KB) * 64); } }
; DI void attn_block(const Params& p, int layer, int hd, int q0, int nkeys, char* smem) {
;     ...
;   for (int kb = 0; kb < nkb; ++kb) {
;     const char* Vs = smem + c0 * ST + KT;
;     A_STORE(c2);
;     A_LOAD((kb + 3 < lastkb) ? kb + 3 : lastkb);
;     if (kb + 1 < nkb) A_SCORES(sn, c1);
;     float mx = fmaxf(sc[0][0], sc[1][0]);
; #pragma unroll
;     for (int i = 1; i < 16; ++i) mx = fmaxf(mx, fmaxf(sc[0][i], sc[1][i]));
;     {
;       const auto pr_ = __builtin_amdgcn_permlane32_swap(__float_as_uint(mx), __float_as_uint(mx), false, false);
;       mx = fmaxf(__uint_as_float(pr_[0]), __uint_as_float(pr_[1]));
;     }
;     if (__any(mx > m + 8.f)) {
;       const float mn = (mx > m + 8.f) ? mx : m;
;       const float alpha = ex2(m - mn);
;       l *= alpha;
; #pragma unroll
;       for (int vt = 0; vt < 4; ++vt)
; #pragma unroll
;         for (int i = 0; i < 16; ++i) o[vt][i] *= alpha;
;       m = mn;
;     }
;     bf16x8 va[2][4];
;     const char* vbase = Vs + r * VROW + 16 * h;
; #pragma unroll
;     for (int vt = 0; vt < 4; ++vt) va[0][vt] = *(const bf16x8*)(vbase + 32 * vt * VROW);
;     float ls[4] = {0.f, 0.f, 0.f, 0.f};
; #pragma unroll
;     for (int st = 0; st < 4; ++st) {
;       if (st < 3) {
; #pragma unroll
;         for (int vt = 0; vt < 4; ++vt) va[(st + 1) & 1][vt] = *(const bf16x8*)(vbase + 32 * vt * VROW + (st + 1) * 32);
;       }
;       float pv[8];
; #pragma unroll
;       for (int i = 0; i < 8; ++i) { pv[i] = ex2(sc[st >> 1][8 * (st & 1) + i] - m); ls[i & 3] += pv[i]; }
;       u32x4 pk; pk.x = pack2(pv[0], pv[1]); pk.y = pack2(pv[2], pv[3]); pk.z = pack2(pv[4], pv[5]); pk.w = pack2(pv[6], pv[7]);
;       const bf16x8 pb = __builtin_bit_cast(bf16x8, pk);
; #pragma unroll
;       for (int vt = 0; vt < 4; ++vt) o[vt] = MFMA32(va[st & 1][vt], pb, o[vt]);
;     }
;     l += (ls[0] + ls[1]) + (ls[2] + ls[3]);
;     __syncthreads();
;     sc[0] = sn[0]; sc[1] = sn[1];
;     { const int tmp = c0; c0 = c1; c1 = c2; c2 = tmp; }
.Lat_top_1:
	s_waitcnt lgkmcnt(5)
	v_mfma_f32_32x32x16_bf16 v[98:113], v[208:211], v[130:133], v[66:81]
	ds_read_b128 v[208:211], v162 offset:96
	s_min_i32 s60, s6, 0x80
	s_add_i32 s60, s60, 3
	v_exp_f32_e32 v246, v82
	v_exp_f32_e32 v247, v83
	v_exp_f32_e32 v248, v84
	v_exp_f32_e32 v249, v85
	v_add_f32_e32 v197, v197, v246
	s_waitcnt lgkmcnt(4)
	v_mfma_f32_32x32x16_bf16 v[98:113], v[212:215], v[134:137], v[98:113]
	s_waitcnt vmcnt(3)
	ds_write_b128 v194, v[158:161] offset:16
	v_lshl_add_u32 v177, s60, 17, v175
	global_load_dwordx4 v[158:161], v177, s[52:53]
	v_add_f32_e32 v207, v207, v247
	v_cvt_pk_bf16_f32 v242, v246, v247
	v_exp_f32_e32 v250, v86
	v_add_f32_e32 v197, v197, v248
	v_add_f32_e32 v207, v207, v249
	s_waitcnt lgkmcnt(3)
	v_mfma_f32_32x32x16_bf16 v[98:113], v[216:219], v[138:141], v[98:113]
	v_cvt_pk_bf16_f32 v243, v248, v249
	v_exp_f32_e32 v251, v87
	v_exp_f32_e32 v237, v88
	v_add_f32_e32 v197, v197, v250
	v_exp_f32_e32 v196, v89
	s_waitcnt lgkmcnt(1)
	v_mfma_f32_32x32x16_bf16 v[98:113], v[208:211], v[142:145], v[98:113]
	v_add_f32_e32 v207, v207, v251
	v_cvt_pk_bf16_f32 v244, v250, v251
	v_cvt_pk_bf16_f32 v245, v237, v196
	v_add_f32_e32 v197, v197, v237
	v_add_f32_e32 v207, v207, v196
	v_mfma_f32_32x32x16_bf16 v[34:49], v[220:223], v[242:245], v[34:49]
	ds_read_b128 v[220:223], v164 offset:32
	v_exp_f32_e32 v246, v90
	v_exp_f32_e32 v247, v91
	v_exp_f32_e32 v248, v92
	v_exp_f32_e32 v249, v93
	v_add_f32_e32 v197, v197, v246
	v_mfma_f32_32x32x16_bf16 v[18:33], v[224:227], v[242:245], v[18:33]
	ds_read_b128 v[224:227], v164 offset:4640
	s_waitcnt vmcnt(3)
	ds_write_b128 v194, v[154:157] offset:8720
	global_load_dwordx4 v[154:157], v177, s[54:55]
	v_add_f32_e32 v207, v207, v247
	v_cvt_pk_bf16_f32 v170, v246, v247
	v_exp_f32_e32 v250, v94
	v_add_f32_e32 v197, v197, v248
	v_add_f32_e32 v207, v207, v249
	v_mfma_f32_32x32x16_bf16 v[2:17], v[228:231], v[242:245], v[2:17]
	ds_read_b128 v[228:231], v164 offset:9248
	v_cvt_pk_bf16_f32 v171, v248, v249
	v_exp_f32_e32 v251, v95
	v_exp_f32_e32 v237, v96
	v_add_f32_e32 v197, v197, v250
	v_exp_f32_e32 v196, v97
	v_mfma_f32_32x32x16_bf16 v[50:65], v[238:241], v[242:245], v[50:65]
	ds_read_b128 v[238:241], v164 offset:13856
	v_add_f32_e32 v207, v207, v251
	v_cvt_pk_bf16_f32 v172, v250, v251
	v_cvt_pk_bf16_f32 v173, v237, v196
	v_add_f32_e32 v197, v197, v237
	v_add_f32_e32 v207, v207, v196
	s_waitcnt lgkmcnt(4)
	v_mfma_f32_32x32x16_bf16 v[34:49], v[220:223], v[170:173], v[34:49]
	ds_read_b128 v[220:223], v164 offset:64
	v_exp_f32_e32 v246, v114
	v_exp_f32_e32 v247, v115
	v_exp_f32_e32 v248, v116
	v_exp_f32_e32 v249, v117
	v_add_f32_e32 v197, v197, v246
	s_waitcnt lgkmcnt(4)
	v_mfma_f32_32x32x16_bf16 v[18:33], v[224:227], v[170:173], v[18:33]
	ds_read_b128 v[224:227], v164 offset:4672
	s_waitcnt vmcnt(3)
	ds_write_b64 v205, v[146:147] offset:17424
	ds_write_b64 v205, v[148:149] offset:17440
	v_lshl_add_u32 v177, s60, 7, v176
	global_load_dwordx4 v[146:149], v177, s[56:57]
	v_add_f32_e32 v207, v207, v247
	v_cvt_pk_bf16_f32 v242, v246, v247
	v_exp_f32_e32 v250, v118
	v_add_f32_e32 v197, v197, v248
	v_add_f32_e32 v207, v207, v249
	s_waitcnt lgkmcnt(5)
	v_mfma_f32_32x32x16_bf16 v[2:17], v[228:231], v[170:173], v[2:17]
	ds_read_b128 v[228:231], v164 offset:9280
	v_cvt_pk_bf16_f32 v243, v248, v249
	v_exp_f32_e32 v251, v119
	v_exp_f32_e32 v237, v120
	v_add_f32_e32 v197, v197, v250
	v_exp_f32_e32 v196, v121
	s_waitcnt lgkmcnt(5)
	v_mfma_f32_32x32x16_bf16 v[50:65], v[238:241], v[170:173], v[50:65]
	ds_read_b128 v[238:241], v164 offset:13888
	v_add_f32_e32 v207, v207, v251
	v_cvt_pk_bf16_f32 v244, v250, v251
	v_cvt_pk_bf16_f32 v245, v237, v196
	v_add_f32_e32 v197, v197, v237
	v_add_f32_e32 v207, v207, v196
	s_waitcnt lgkmcnt(5)
	v_mfma_f32_32x32x16_bf16 v[34:49], v[220:223], v[242:245], v[34:49]
	ds_read_b128 v[220:223], v164 offset:96
	ds_read_b128 v[212:215], v162 offset:8704
	v_exp_f32_e32 v246, v122
	v_exp_f32_e32 v247, v123
	v_exp_f32_e32 v248, v124
	v_exp_f32_e32 v249, v125
	v_add_f32_e32 v197, v197, v246
	s_waitcnt lgkmcnt(6)
	v_mfma_f32_32x32x16_bf16 v[18:33], v[224:227], v[242:245], v[18:33]
	ds_read_b128 v[224:227], v164 offset:4704
	s_waitcnt vmcnt(3)
	ds_write_b64 v205, v[150:151] offset:26640
	ds_write_b64 v205, v[152:153] offset:26656
	global_load_dwordx4 v[150:153], v177, s[58:59]
	ds_read_b128 v[216:219], v162 offset:8736
	v_add_f32_e32 v207, v207, v247
	v_cvt_pk_bf16_f32 v170, v246, v247
	v_exp_f32_e32 v250, v126
	v_add_f32_e32 v197, v197, v248
	v_add_f32_e32 v207, v207, v249
	s_waitcnt lgkmcnt(7)
	v_mfma_f32_32x32x16_bf16 v[2:17], v[228:231], v[242:245], v[2:17]
	ds_read_b128 v[228:231], v164 offset:9312
	ds_read_b128 v[208:211], v162 offset:8768
	v_cvt_pk_bf16_f32 v171, v248, v249
	v_exp_f32_e32 v251, v127
	v_exp_f32_e32 v237, v128
	v_add_f32_e32 v197, v197, v250
	v_exp_f32_e32 v196, v129
	s_waitcnt lgkmcnt(8)
	v_mfma_f32_32x32x16_bf16 v[50:65], v[238:241], v[242:245], v[50:65]
	ds_read_b128 v[238:241], v164 offset:13920
	v_add_f32_e32 v207, v207, v251
	v_cvt_pk_bf16_f32 v172, v250, v251
	v_cvt_pk_bf16_f32 v173, v237, v196
	v_add_f32_e32 v197, v197, v237
	v_add_f32_e32 v207, v207, v196
	s_waitcnt lgkmcnt(7)
	v_mfma_f32_32x32x16_bf16 v[82:97], v[212:215], v[130:133], v[66:81]
	ds_read_b128 v[212:215], v162 offset:8800
	v_max3_f32 v246, v98, v99, v100
	s_waitcnt lgkmcnt(4)
	v_mfma_f32_32x32x16_bf16 v[82:97], v[216:219], v[134:137], v[82:97]
	v_max3_f32 v247, v101, v102, v103
	s_waitcnt lgkmcnt(2)
	v_mfma_f32_32x32x16_bf16 v[82:97], v[208:211], v[138:141], v[82:97]
	v_max3_f32 v246, v246, v104, v105
	s_waitcnt lgkmcnt(0)
	v_mfma_f32_32x32x16_bf16 v[82:97], v[212:215], v[142:145], v[82:97]
	v_max3_f32 v247, v247, v106, v107
	s_waitcnt lgkmcnt(0)
	s_barrier
	v_mfma_f32_32x32x16_bf16 v[34:49], v[220:223], v[170:173], v[34:49]
	ds_read_b128 v[220:223], v164 offset:35840
	ds_read_b128 v[208:211], v206 offset:0
	v_max3_f32 v246, v246, v108, v109
	v_max3_f32 v247, v247, v110, v111
	v_mfma_f32_32x32x16_bf16 v[18:33], v[224:227], v[170:173], v[18:33]
	ds_read_b128 v[224:227], v164 offset:40448
	ds_read_b128 v[212:215], v206 offset:32
	v_max3_f32 v246, v246, v112, v113
	v_mfma_f32_32x32x16_bf16 v[2:17], v[228:231], v[170:173], v[2:17]
	ds_read_b128 v[228:231], v164 offset:45056
	ds_read_b128 v[216:219], v206 offset:64
	v_max3_f32 v247, v247, v82, v83
	v_max3_f32 v246, v246, v84, v85
	v_max3_f32 v247, v247, v86, v87
	v_max3_f32 v246, v246, v88, v89
	v_mfma_f32_32x32x16_bf16 v[50:65], v[238:241], v[170:173], v[50:65]
	ds_read_b128 v[238:241], v164 offset:49664
	v_max3_f32 v247, v247, v90, v91
	v_max3_f32 v246, v246, v92, v93
	v_max3_f32 v247, v247, v94, v95
	v_max3_f32 v246, v246, v96, v97
	v_max_f32_e32 v246, v246, v247
	v_mov_b32_e32 v247, v246
	s_nop 1
	v_permlane32_swap_b32_e32 v246, v247
	v_max_f32_e32 v246, v246, v247
	v_cmp_lt_f32_e32 vcc, 0x41000000, v246
	s_cbranch_vccnz .Lat_rare_1

; #define MFMA32(a, b, c) __builtin_amdgcn_mfma_f32_32x32x16_bf16((a), (b), (c), 0, 0, 0)
; DI float ex2(float x) { return __builtin_amdgcn_exp2f(x); }
; #define A_LOAD(KB) { _Pragma("unroll") for (int i = 0; i < 2; ++i) { rk[i] = *(const u32x4*)(kp + (size_t)((KB) * 64 + 32 * i) * 1024); rv[i] = *(const u32x4*)(vp + (size_t)(64 * i) * TOK + (KB) * 64); } }
; DI void attn_block(const Params& p, int layer, int hd, int q0, int nkeys, char* smem) {
;     ...
;   for (int kb = 0; kb < nkb; ++kb) {
;     const char* Vs = smem + c0 * ST + KT;
;     A_STORE(c2);
;     A_LOAD((kb + 3 < lastkb) ? kb + 3 : lastkb);
;     if (kb + 1 < nkb) A_SCORES(sn, c1);
;     float mx = fmaxf(sc[0][0], sc[1][0]);
; #pragma unroll
;     for (int i = 1; i < 16; ++i) mx = fmaxf(mx, fmaxf(sc[0][i], sc[1][i]));
;     {
;       const auto pr_ = __builtin_amdgcn_permlane32_swap(__float_as_uint(mx), __float_as_uint(mx), false, false);
;       mx = fmaxf(__uint_as_float(pr_[0]), __uint_as_float(pr_[1]));
;     }
;     if (__any(mx > m + 8.f)) {
;       const float mn = (mx > m + 8.f) ? mx : m;
;       const float alpha = ex2(m - mn);
;       l *= alpha;
; #pragma unroll
;       for (int vt = 0; vt < 4; ++vt)
; #pragma unroll
;         for (int i = 0; i < 16; ++i) o[vt][i] *= alpha;
;       m = mn;
;     }
;     bf16x8 va[2][4];
;     const char* vbase = Vs + r * VROW + 16 * h;
; #pragma unroll
;     for (int vt = 0; vt < 4; ++vt) va[0][vt] = *(const bf16x8*)(vbase + 32 * vt * VROW);
;     float ls[4] = {0.f, 0.f, 0.f, 0.f};
; #pragma unroll
;     for (int st = 0; st < 4; ++st) {
;       if (st < 3) {
; #pragma unroll
;         for (int vt = 0; vt < 4; ++vt) va[(st + 1) & 1][vt] = *(const bf16x8*)(vbase + 32 * vt * VROW + (st + 1) * 32);
;       }
;       float pv[8];
; #pragma unroll
;       for (int i = 0; i < 8; ++i) { pv[i] = ex2(sc[st >> 1][8 * (st & 1) + i] - m); ls[i & 3] += pv[i]; }
;       u32x4 pk; pk.x = pack2(pv[0], pv[1]); pk.y = pack2(pv[2], pv[3]); pk.z = pack2(pv[4], pv[5]); pk.w = pack2(pv[6], pv[7]);
;       const bf16x8 pb = __builtin_bit_cast(bf16x8, pk);
; #pragma unroll
;       for (int vt = 0; vt < 4; ++vt) o[vt] = MFMA32(va[st & 1][vt], pb, o[vt]);
;     }
;     l += (ls[0] + ls[1]) + (ls[2] + ls[3]);
;     __syncthreads();
;     sc[0] = sn[0]; sc[1] = sn[1];
;     { const int tmp = c0; c0 = c1; c1 = c2; c2 = tmp; }
.Lat_top_2:
	s_waitcnt lgkmcnt(5)
	v_mfma_f32_32x32x16_bf16 v[114:129], v[208:211], v[130:133], v[66:81]
	ds_read_b128 v[208:211], v206 offset:96
	s_min_i32 s60, s6, 0x80
	s_add_i32 s60, s60, 3
	v_exp_f32_e32 v246, v98
	v_exp_f32_e32 v247, v99
	v_exp_f32_e32 v248, v100
	v_exp_f32_e32 v249, v101
	v_add_f32_e32 v197, v197, v246
	s_waitcnt lgkmcnt(4)
	v_mfma_f32_32x32x16_bf16 v[114:129], v[212:215], v[134:137], v[114:129]
	s_waitcnt vmcnt(3)
	ds_write_b128 v194, v[158:161] offset:35856
	v_lshl_add_u32 v177, s60, 17, v175
	global_load_dwordx4 v[158:161], v177, s[52:53]
	v_add_f32_e32 v207, v207, v247
	v_cvt_pk_bf16_f32 v242, v246, v247
	v_exp_f32_e32 v250, v102
	v_add_f32_e32 v197, v197, v248
	v_add_f32_e32 v207, v207, v249
	s_waitcnt lgkmcnt(3)
	v_mfma_f32_32x32x16_bf16 v[114:129], v[216:219], v[138:141], v[114:129]
	v_cvt_pk_bf16_f32 v243, v248, v249
	v_exp_f32_e32 v251, v103
	v_exp_f32_e32 v237, v104
	v_add_f32_e32 v197, v197, v250
	v_exp_f32_e32 v196, v105
	s_waitcnt lgkmcnt(1)
	v_mfma_f32_32x32x16_bf16 v[114:129], v[208:211], v[142:145], v[114:129]
	v_add_f32_e32 v207, v207, v251
	v_cvt_pk_bf16_f32 v244, v250, v251
	v_cvt_pk_bf16_f32 v245, v237, v196
	v_add_f32_e32 v197, v197, v237
	v_add_f32_e32 v207, v207, v196
	v_mfma_f32_32x32x16_bf16 v[34:49], v[220:223], v[242:245], v[34:49]
	ds_read_b128 v[220:223], v164 offset:35872
	v_exp_f32_e32 v246, v106
	v_exp_f32_e32 v247, v107
	v_exp_f32_e32 v248, v108
	v_exp_f32_e32 v249, v109
	v_add_f32_e32 v197, v197, v246
	v_mfma_f32_32x32x16_bf16 v[18:33], v[224:227], v[242:245], v[18:33]
	ds_read_b128 v[224:227], v164 offset:40480
	s_waitcnt vmcnt(3)
	ds_write_b128 v194, v[154:157] offset:44560
	global_load_dwordx4 v[154:157], v177, s[54:55]
	v_add_f32_e32 v207, v207, v247
	v_cvt_pk_bf16_f32 v170, v246, v247
	v_exp_f32_e32 v250, v110
	v_add_f32_e32 v197, v197, v248
	v_add_f32_e32 v207, v207, v249
	v_mfma_f32_32x32x16_bf16 v[2:17], v[228:231], v[242:245], v[2:17]
	ds_read_b128 v[228:231], v164 offset:45088
	v_cvt_pk_bf16_f32 v171, v248, v249
	v_exp_f32_e32 v251, v111
	v_exp_f32_e32 v237, v112
	v_add_f32_e32 v197, v197, v250
	v_exp_f32_e32 v196, v113
	v_mfma_f32_32x32x16_bf16 v[50:65], v[238:241], v[242:245], v[50:65]
	ds_read_b128 v[238:241], v164 offset:49696
	v_add_f32_e32 v207, v207, v251
	v_cvt_pk_bf16_f32 v172, v250, v251
	v_cvt_pk_bf16_f32 v173, v237, v196
	v_add_f32_e32 v197, v197, v237
	v_add_f32_e32 v207, v207, v196
	s_waitcnt lgkmcnt(4)
	v_mfma_f32_32x32x16_bf16 v[34:49], v[220:223], v[170:173], v[34:49]
	ds_read_b128 v[220:223], v164 offset:35904
	v_exp_f32_e32 v246, v82
	v_exp_f32_e32 v247, v83
	v_exp_f32_e32 v248, v84
	v_exp_f32_e32 v249, v85
	v_add_f32_e32 v197, v197, v246
	s_waitcnt lgkmcnt(4)
	v_mfma_f32_32x32x16_bf16 v[18:33], v[224:227], v[170:173], v[18:33]
	ds_read_b128 v[224:227], v164 offset:40512
	s_waitcnt vmcnt(3)
	ds_write_b64 v205, v[146:147] offset:53264
	ds_write_b64 v205, v[148:149] offset:53280
	v_lshl_add_u32 v177, s60, 7, v176
	global_load_dwordx4 v[146:149], v177, s[56:57]
	v_add_f32_e32 v207, v207, v247
	v_cvt_pk_bf16_f32 v242, v246, v247
	v_exp_f32_e32 v250, v86
	v_add_f32_e32 v197, v197, v248
	v_add_f32_e32 v207, v207, v249
	s_waitcnt lgkmcnt(5)
	v_mfma_f32_32x32x16_bf16 v[2:17], v[228:231], v[170:173], v[2:17]
	ds_read_b128 v[228:231], v164 offset:45120
	v_cvt_pk_bf16_f32 v243, v248, v249
	v_exp_f32_e32 v251, v87
	v_exp_f32_e32 v237, v88
	v_add_f32_e32 v197, v197, v250
	v_exp_f32_e32 v196, v89
	s_waitcnt lgkmcnt(5)
	v_mfma_f32_32x32x16_bf16 v[50:65], v[238:241], v[170:173], v[50:65]
	ds_read_b128 v[238:241], v164 offset:49728
	v_add_f32_e32 v207, v207, v251
	v_cvt_pk_bf16_f32 v244, v250, v251
	v_cvt_pk_bf16_f32 v245, v237, v196
	v_add_f32_e32 v197, v197, v237
	v_add_f32_e32 v207, v207, v196
	s_waitcnt lgkmcnt(5)
	v_mfma_f32_32x32x16_bf16 v[34:49], v[220:223], v[242:245], v[34:49]
	ds_read_b128 v[220:223], v164 offset:35936
	ds_read_b128 v[212:215], v206 offset:8704
	v_exp_f32_e32 v246, v90
	v_exp_f32_e32 v247, v91
	v_exp_f32_e32 v248, v92
	v_exp_f32_e32 v249, v93
	v_add_f32_e32 v197, v197, v246
	s_waitcnt lgkmcnt(6)
	v_mfma_f32_32x32x16_bf16 v[18:33], v[224:227], v[242:245], v[18:33]
	ds_read_b128 v[224:227], v164 offset:40544
	s_waitcnt vmcnt(3)
	ds_write_b64 v205, v[150:151] offset:62480
	ds_write_b64 v205, v[152:153] offset:62496
	global_load_dwordx4 v[150:153], v177, s[58:59]
	ds_read_b128 v[216:219], v206 offset:8736
	v_add_f32_e32 v207, v207, v247
	v_cvt_pk_bf16_f32 v170, v246, v247
	v_exp_f32_e32 v250, v94
	v_add_f32_e32 v197, v197, v248
	v_add_f32_e32 v207, v207, v249
	s_waitcnt lgkmcnt(7)
	v_mfma_f32_32x32x16_bf16 v[2:17], v[228:231], v[242:245], v[2:17]
	ds_read_b128 v[228:231], v164 offset:45152
	ds_read_b128 v[208:211], v206 offset:8768
	v_cvt_pk_bf16_f32 v171, v248, v249
	v_exp_f32_e32 v251, v95
	v_exp_f32_e32 v237, v96
	v_add_f32_e32 v197, v197, v250
	v_exp_f32_e32 v196, v97
	s_waitcnt lgkmcnt(8)
	v_mfma_f32_32x32x16_bf16 v[50:65], v[238:241], v[242:245], v[50:65]
	ds_read_b128 v[238:241], v164 offset:49760
	v_add_f32_e32 v207, v207, v251
	v_cvt_pk_bf16_f32 v172, v250, v251
	v_cvt_pk_bf16_f32 v173, v237, v196
	v_add_f32_e32 v197, v197, v237
	v_add_f32_e32 v207, v207, v196
	s_waitcnt lgkmcnt(7)
	v_mfma_f32_32x32x16_bf16 v[98:113], v[212:215], v[130:133], v[66:81]
	ds_read_b128 v[212:215], v206 offset:8800
	v_max3_f32 v246, v114, v115, v116
	s_waitcnt lgkmcnt(4)
	v_mfma_f32_32x32x16_bf16 v[98:113], v[216:219], v[134:137], v[98:113]
	v_max3_f32 v247, v117, v118, v119
	s_waitcnt lgkmcnt(2)
	v_mfma_f32_32x32x16_bf16 v[98:113], v[208:211], v[138:141], v[98:113]
	v_max3_f32 v246, v246, v120, v121
	s_waitcnt lgkmcnt(0)
	v_mfma_f32_32x32x16_bf16 v[98:113], v[212:215], v[142:145], v[98:113]
	v_max3_f32 v247, v247, v122, v123
	s_waitcnt lgkmcnt(0)
	s_barrier
	v_mfma_f32_32x32x16_bf16 v[34:49], v[220:223], v[170:173], v[34:49]
	ds_read_b128 v[220:223], v163 offset:17408
	ds_read_b128 v[208:211], v206 offset:35840
	v_max3_f32 v246, v246, v124, v125
	v_max3_f32 v247, v247, v126, v127
	v_mfma_f32_32x32x16_bf16 v[18:33], v[224:227], v[170:173], v[18:33]
	ds_read_b128 v[224:227], v163 offset:22016
	ds_read_b128 v[212:215], v206 offset:35872
	v_max3_f32 v246, v246, v128, v129
	v_mfma_f32_32x32x16_bf16 v[2:17], v[228:231], v[170:173], v[2:17]
	ds_read_b128 v[228:231], v163 offset:26624
	ds_read_b128 v[216:219], v206 offset:35904
	v_max3_f32 v247, v247, v98, v99
	v_max3_f32 v246, v246, v100, v101
	v_max3_f32 v247, v247, v102, v103
	v_max3_f32 v246, v246, v104, v105
	v_mfma_f32_32x32x16_bf16 v[50:65], v[238:241], v[170:173], v[50:65]
	ds_read_b128 v[238:241], v163 offset:31232
	v_max3_f32 v247, v247, v106, v107
	v_max3_f32 v246, v246, v108, v109
	v_max3_f32 v247, v247, v110, v111
	v_max3_f32 v246, v246, v112, v113
	v_max_f32_e32 v246, v246, v247
	v_mov_b32_e32 v247, v246
	s_nop 1
	v_permlane32_swap_b32_e32 v246, v247
	v_max_f32_e32 v246, v246, v247
	v_cmp_lt_f32_e32 vcc, 0x41000000, v246
	s_cbranch_vccnz .Lat_rare_2

; DI void attn_block(const Params& p, int layer, int hd, int q0, int nkeys, char* smem) {
;     ...
;     l += (ls[0] + ls[1]) + (ls[2] + ls[3]);
;     __syncthreads();
;     sc[0] = sn[0]; sc[1] = sn[1];
;     { const int tmp = c0; c0 = c1; c1 = c2; c2 = tmp; }
;   }
;     ...
;   l += __shfl_xor(l, 32);
;   const float scl = (mp == 0 ? 1.f : scal[16 + layer]) / l;
.Lat_exit:
	s_waitcnt vmcnt(0)
	s_waitcnt lgkmcnt(0)
	v_mov_b64_e32 v[66:67], v[82:83]
	v_mov_b64_e32 v[68:69], v[84:85]
	v_mov_b64_e32 v[70:71], v[86:87]
	v_mov_b64_e32 v[72:73], v[88:89]
	v_mov_b64_e32 v[74:75], v[90:91]
	v_mov_b64_e32 v[76:77], v[92:93]
	v_mov_b64_e32 v[78:79], v[94:95]
	v_mov_b64_e32 v[80:81], v[96:97]
	v_mov_b64_e32 v[82:83], v[98:99]
	v_mov_b64_e32 v[84:85], v[100:101]
	v_mov_b64_e32 v[86:87], v[102:103]
	v_mov_b64_e32 v[88:89], v[104:105]
	v_mov_b64_e32 v[90:91], v[106:107]
	v_mov_b64_e32 v[92:93], v[108:109]
	v_mov_b64_e32 v[94:95], v[110:111]
	v_mov_b64_e32 v[96:97], v[112:113]
	v_add_f32_e32 v195, v197, v207
	v_mov_b32_e32 v204, 0
	v_mov_b32_e32 v196, 0x1a410
	v_lshl_add_u32 v196, v0, 2, v196
	ds_read_b32 v170, v196 offset:0
	ds_read_b32 v171, v196 offset:2048
	ds_read_b32 v172, v196 offset:4096
	ds_read_b32 v173, v196 offset:6144
	ds_read_b32 v174, v196 offset:8192
	ds_read_b32 v175, v196 offset:10240
	ds_read_b32 v176, v196 offset:12288
	ds_read_b32 v177, v196 offset:14336
	s_mov_b32 s7, 1
	s_mov_b32 s42, 2
	s_mov_b32 s4, 0x11800
	s_mov_b32 s8, 0x8c10
	s_movk_i32 s6, 0x83
	s_waitcnt lgkmcnt(0)
	s_branch .LBB0_400

; DI int tid512() { int t = threadIdx.x; asm volatile("" : "+v"(t)); return t; }
; DI unsigned voff256(size_t ld) { const int t = tid512(); return (unsigned)(((size_t)(t >> 3) * ld + (t & 7) * 8) * 2); }
; DI void gemm256(const char* a_u, unsigned a_voff, size_t astep, const char* b_u, unsigned b_voff, size_t bstep, int nk, char* smem, f32x16 (&acc)[4][2]) {
;   asm volatile("" : "+s"(nk));
;   const int t = tid512(), lane = t & 63, w = t >> 6, wm = w >> 2, wn = w & 3, r = lane & 31, h = lane >> 5;
;   const int soff = (t >> 3) * LROW + (t & 7) * 16;
;   const int aoff = (128 * wm + r) * LROW + h * 16, boff = T2 + (64 * wn + r) * LROW + h * 16;
;   u32x4 ra[4], rb[4];
; #pragma unroll
;   for (int i = 0; i < 4; ++i) { ra[i] = *(const u32x4*)(a_u + i * astep + a_voff); rb[i] = *(const u32x4*)(b_u + i * bstep + b_voff); }
;   __syncthreads();
; #pragma unroll
;   for (int i = 0; i < 4; ++i) { *(u32x4*)(smem + soff + i * 64 * LROW) = ra[i]; *(u32x4*)(smem + T2 + soff + i * 64 * LROW) = rb[i]; }
;   const int last = nk - 1;
;   {
;     const int k1 = last < 1 ? last : 1;
; #pragma unroll
;     for (int i = 0; i < 4; ++i) { ra[i] = *(const u32x4*)(a_u + i * astep + k1 * 128 + a_voff); rb[i] = *(const u32x4*)(b_u + i * bstep + k1 * 128 + b_voff); }
;   }
;   __syncthreads();
; DI void gateup256(const Params& p, int layer, char* smem) {
;     ...
;   for (int i = 0;; ++i) {
;     const int L = tile_of(i, 32 * 44);
;     if (L < 0) break;
;     int tm, nb; tile_mn(L, 32, 44, tm, nb);
;     const int t = tid512(), lane = t & 63, w = t >> 6, wm = w >> 2, wn = w & 3, r = lane & 31, h = lane >> 5;
;     const unsigned bvo = (unsigned)(((size_t)((t >> 3) & 31) * DM + (t & 7) * 8) * 2 + ((((t >> 3) >> 5) & 1) ? (O_WU - O_WG) : 0));
;     f32x16 acc[4][2]; zero_acc256(acc);
;     gemm256((const char*)(H + (size_t)(256 + tm * 256) * DM), voff256(DM), (size_t)128 * DM, (const char*)(WG + (size_t)(nb * 128) * DM), bvo, (size_t)64 * DM, DM / 64, smem, acc);
.LBB0_1564:
	s_mul_hi_u32 s4, s6, 0xba2e8ba3
	s_lshr_b32 s4, s4, 7
	s_lshl_b32 s5, s4, 2
	s_sub_i32 s7, 32, s5
	s_min_i32 s7, s7, 4
	s_abs_i32 s9, s7
	v_cvt_f32_u32_e32 v2, s9
	s_sub_i32 s10, 0, s9
	s_mulk_i32 s4, 0xff50
	s_add_i32 s4, s4, s6
	v_rcp_iflag_f32_e32 v2, v2
	s_abs_i32 s8, s4
	s_xor_b32 s6, s4, s7
	s_ashr_i32 s6, s6, 31
	v_mul_f32_e32 v2, 0x4f7ffffe, v2
	v_cvt_u32_f32_e32 v2, v2
	v_mov_b32_e32 v193, v0
	v_mov_b32_e32 v37, v181
	v_readfirstlane_b32 s11, v2
	s_mul_i32 s10, s10, s11
	s_mul_hi_u32 s10, s11, s10
	s_add_i32 s11, s11, s10
	s_mul_hi_u32 s10, s8, s11
	s_mul_i32 s11, s10, s9
	s_sub_i32 s8, s8, s11
	s_add_i32 s11, s10, 1
	s_sub_i32 s15, s8, s9
	s_cmp_ge_u32 s8, s9
	s_cselect_b32 s10, s11, s10
	s_cselect_b32 s8, s15, s8
	s_add_i32 s11, s10, 1
	s_cmp_ge_u32 s8, s9
	s_cselect_b32 s8, s11, s10
	s_xor_b32 s8, s8, s6
	s_sub_i32 s6, s8, s6
	s_mul_i32 s7, s6, s7
	s_sub_i32 s4, s4, s7
	s_add_i32 s4, s4, s5
	s_lshl_b32 s4, s4, 8
	s_addk_i32 s4, 0x100
	v_lshlrev_b32_e32 v2, 9, v193
	v_lshlrev_b32_e32 v3, 4, v193
	v_bfe_i32 v4, v193, 8, 1
	s_ashr_i32 s5, s4, 31
	v_and_b32_e32 v2, 0x1f000, v2
	v_and_b32_e32 v3, 0x70, v3
	v_and_b32_e32 v4, 0x2c00000, v4
	s_lshl_b64 s[8:9], s[4:5], 12
	v_or3_b32 v36, v2, v3, v4
	s_add_u32 s8, s92, s8
	v_mov_b32_e32 v2, v0
	s_addc_u32 s9, s93, s9
	s_lshl_b32 s6, s6, 7
	v_lshlrev_b32_e32 v3, 4, v2
	v_and_b32_e32 v3, 0x70, v3
	v_lshlrev_b32_e32 v2, 9, v2
	s_movk_i32 s5, 0xf000
	s_ashr_i32 s7, s6, 31
	v_and_or_b32 v180, v2, s5, v3
	s_lshl_b64 s[10:11], s[6:7], 12
	s_add_u32 s10, s12, s10
	v_lshl_add_u64 v[162:163], s[8:9], 0, v[180:181]
	s_addc_u32 s11, s13, s11
	v_add_co_u32_e32 v12, vcc, s84, v162
	v_lshl_add_u64 v[164:165], s[10:11], 0, v[36:37]
	s_nop 0
	v_addc_co_u32_e32 v13, vcc, 0, v163, vcc
	v_add_co_u32_e32 v16, vcc, s87, v164
	s_mov_b32 s5, 32
	v_mov_b32_e32 v2, v0
	v_addc_co_u32_e32 v17, vcc, 0, v165, vcc
	v_add_co_u32_e32 v20, vcc, s31, v162
	v_lshlrev_b32_e32 v4, 4, v2
	v_and_b32_e32 v38, 0x70, v4
	v_lshrrev_b32_e32 v132, 6, v0
	s_nop 0
	v_readfirstlane_b32 s61, v132
	v_and_b32_e32 v132, 63, v0
	v_and_b32_e32 v133, 31, v132
	v_lshrrev_b32_e32 v136, 5, v132
	v_bfe_u32 v137, v133, 1, 3
	v_lshlrev_b32_e32 v133, 7, v133
	s_lshr_b32 s60, s61, 2
	s_lshl_b32 s60, s60, 14
	s_add_i32 s60, s60, 16
	s_and_b32 s62, s61, 3
	s_lshl_b32 s62, s62, 13
	s_add_i32 s62, s62, 0x10010
	v_add_u32_e32 v194, 0, v136
	v_xor_b32_e32 v194, v194, v137
	v_lshl_add_u32 v194, v194, 4, v133
	v_add_u32_e32 v160, s62, v194
	v_add_u32_e32 v194, s60, v194
	v_add_u32_e32 v195, 2, v136
	v_xor_b32_e32 v195, v195, v137
	v_lshl_add_u32 v195, v195, 4, v133
	v_add_u32_e32 v161, s62, v195
	v_add_u32_e32 v195, s60, v195
	v_add_u32_e32 v250, 4, v136
	v_xor_b32_e32 v250, v250, v137
	v_lshl_add_u32 v250, v250, 4, v133
	v_add_u32_e32 v162, s62, v250
	v_add_u32_e32 v250, s60, v250
	v_add_u32_e32 v251, 6, v136
	v_xor_b32_e32 v251, v251, v137
	v_lshl_add_u32 v251, v251, 4, v133
	v_add_u32_e32 v163, s62, v251
	v_add_u32_e32 v251, s60, v251
	v_lshrrev_b32_e32 v133, 3, v132
	s_mov_b32 s60, 0x1000
	v_mul_lo_u32 v133, v133, s60
	v_and_b32_e32 v136, 7, v132
	v_lshrrev_b32_e32 v137, 4, v132
	v_xor_b32_e32 v164, v137, v136
	v_lshl_add_u32 v164, v164, 4, v133
	v_add_u32_e32 v165, 4, v137
	v_xor_b32_e32 v165, v165, v136
	v_lshl_add_u32 v165, v165, 4, v133
	v_add_u32_e32 v165, 0x8000, v165
	v_xor_b32_e32 v130, v137, v136
	v_lshl_add_u32 v130, v130, 4, v133
	v_add_u32_e32 v130, 0x10000, v130
	v_add_u32_e32 v131, 4, v137
	v_xor_b32_e32 v131, v131, v136
	v_lshl_add_u32 v131, v131, 4, v133
	v_add_u32_e32 v131, 0x18000, v131
	s_mul_i32 s60, s61, 0x20000
	s_add_u32 s52, s8, s60
	s_addc_u32 s53, s9, 0
	s_lshr_b32 s60, s61, 1
	s_mul_i32 s60, s60, 0x20000
	s_and_b32 s62, s61, 1
	s_mul_i32 s62, s62, 0x2c00000
	s_add_u32 s60, s60, s62
	s_add_u32 s54, s10, s60
	s_addc_u32 s55, s11, 0
	s_lshl_b32 s58, s61, 12
	s_add_i32 s58, s58, 16
	s_add_i32 s59, s58, 0x10000
	s_mov_b32 s56, 0
	s_mov_b32 s57, 31
	s_barrier
	s_add_u32 m0, s58, 0x0
	s_nop 0
	global_load_lds_dwordx4 v164, s[52:53]
	s_add_u32 m0, s58, 0x400
	s_nop 0
	global_load_lds_dwordx4 v165, s[52:53]
	s_add_u32 m0, s58, 0x800
	s_nop 0
	global_load_lds_dwordx4 v130, s[52:53]
	s_add_u32 m0, s58, 0xc00
	s_nop 0
	global_load_lds_dwordx4 v131, s[52:53]
	s_add_u32 m0, s59, 0x0
	s_nop 0
	global_load_lds_dwordx4 v164, s[54:55]
	s_add_u32 m0, s59, 0x400
	s_nop 0
	global_load_lds_dwordx4 v165, s[54:55]
	s_add_u32 m0, s59, 0x800
	s_nop 0
	global_load_lds_dwordx4 v130, s[54:55]
	s_add_u32 m0, s59, 0xc00
	s_nop 0
	global_load_lds_dwordx4 v131, s[54:55]
	s_cmp_lt_u32 s56, s57
	s_cselect_b32 s60, 0x80, 0
	s_add_u32 s52, s52, s60
	s_addc_u32 s53, s53, 0
	s_add_u32 s54, s54, s60
	s_addc_u32 s55, s55, 0
	v_mov_b64_e32 v[114:115], 0
	v_mov_b64_e32 v[116:117], 0
	v_mov_b64_e32 v[118:119], 0
	v_mov_b64_e32 v[120:121], 0
	v_mov_b64_e32 v[122:123], 0
	v_mov_b64_e32 v[124:125], 0
	v_mov_b64_e32 v[126:127], 0
	v_mov_b64_e32 v[128:129], 0
	v_mov_b64_e32 v[98:99], 0
	v_mov_b64_e32 v[100:101], 0
	v_mov_b64_e32 v[102:103], 0
	v_mov_b64_e32 v[104:105], 0
	v_mov_b64_e32 v[106:107], 0
	v_mov_b64_e32 v[108:109], 0
	v_mov_b64_e32 v[110:111], 0
	v_mov_b64_e32 v[112:113], 0
	v_mov_b64_e32 v[82:83], 0
	v_mov_b64_e32 v[84:85], 0
	v_mov_b64_e32 v[86:87], 0
	v_mov_b64_e32 v[88:89], 0
	v_mov_b64_e32 v[90:91], 0
	v_mov_b64_e32 v[92:93], 0
	v_mov_b64_e32 v[94:95], 0
	v_mov_b64_e32 v[96:97], 0
	v_mov_b64_e32 v[66:67], 0
	v_mov_b64_e32 v[68:69], 0
	v_mov_b64_e32 v[70:71], 0
	v_mov_b64_e32 v[72:73], 0
	v_mov_b64_e32 v[74:75], 0
	v_mov_b64_e32 v[76:77], 0
	v_mov_b64_e32 v[78:79], 0
	v_mov_b64_e32 v[80:81], 0
	v_mov_b64_e32 v[50:51], 0
	v_mov_b64_e32 v[52:53], 0
	v_mov_b64_e32 v[54:55], 0
	v_mov_b64_e32 v[56:57], 0
	v_mov_b64_e32 v[58:59], 0
	v_mov_b64_e32 v[60:61], 0
	v_mov_b64_e32 v[62:63], 0
	v_mov_b64_e32 v[64:65], 0
	v_mov_b64_e32 v[34:35], 0
	v_mov_b64_e32 v[36:37], 0
	v_mov_b64_e32 v[38:39], 0
	v_mov_b64_e32 v[40:41], 0
	v_mov_b64_e32 v[42:43], 0
	v_mov_b64_e32 v[44:45], 0
	v_mov_b64_e32 v[46:47], 0
	v_mov_b64_e32 v[48:49], 0
	v_mov_b64_e32 v[18:19], 0
	v_mov_b64_e32 v[20:21], 0
	v_mov_b64_e32 v[22:23], 0
	v_mov_b64_e32 v[24:25], 0
	v_mov_b64_e32 v[26:27], 0
	v_mov_b64_e32 v[28:29], 0
	v_mov_b64_e32 v[30:31], 0
	v_mov_b64_e32 v[32:33], 0
	v_mov_b64_e32 v[2:3], 0
	v_mov_b64_e32 v[4:5], 0
	v_mov_b64_e32 v[6:7], 0
	v_mov_b64_e32 v[8:9], 0
	v_mov_b64_e32 v[10:11], 0
	v_mov_b64_e32 v[12:13], 0
	v_mov_b64_e32 v[14:15], 0
	v_mov_b64_e32 v[16:17], 0
	s_waitcnt vmcnt(0)
	s_barrier
	ds_read_b128 v[196:199], v194 offset:0
	ds_read_b128 v[212:215], v160 offset:0
	ds_read_b128 v[216:219], v160 offset:4096
	ds_read_b128 v[200:203], v194 offset:4096
	ds_read_b128 v[204:207], v194 offset:8192
	ds_read_b128 v[208:211], v194 offset:12288
; #define MFMA32(a, b, c) __builtin_amdgcn_mfma_f32_32x32x16_bf16((a), (b), (c), 0, 0, 0)
; DI void gemm256(const char* a_u, unsigned a_voff, size_t astep, const char* b_u, unsigned b_voff, size_t bstep, int nk, char* smem, f32x16 (&acc)[4][2]) {
;     ...
;   for (int kt = 0; kt < nk; ++kt) {
;     const int cur = kt & 1, k2 = (kt + 2 < last) ? kt + 2 : last;
;     const char* S = smem + cur * 2 * T2;
;     char* D = smem + (cur ^ 1) * 2 * T2;
;     const char* an = a_u + (size_t)k2 * 128;
;     const char* bn = b_u + (size_t)k2 * 128;
; #pragma unroll
;     for (int s = 0; s < 4; ++s) {
;       bf16x8 a[4], b[2];
; #pragma unroll
;       for (int mi = 0; mi < 4; ++mi) a[mi] = *(const bf16x8*)(S + aoff + mi * 32 * LROW + s * 32);
; #pragma unroll
;       for (int ni = 0; ni < 2; ++ni) b[ni] = *(const bf16x8*)(S + boff + ni * 32 * LROW + s * 32);
;       *(u32x4*)(D + soff + s * 64 * LROW) = ra[s];
;       *(u32x4*)(D + T2 + soff + s * 64 * LROW) = rb[s];
;       ra[s] = *(const u32x4*)(an + s * astep + a_voff);
;       rb[s] = *(const u32x4*)(bn + s * bstep + b_voff);
; #pragma unroll
;       for (int mi = 0; mi < 4; ++mi)
; #pragma unroll
;         for (int ni = 0; ni < 2; ++ni) acc[mi][ni] = MFMA32(a[mi], b[ni], acc[mi][ni]);
;     }
.Lg_gateup_loop:
	s_add_i32 s56, s56, 1
	s_waitcnt lgkmcnt(0)
	v_mfma_f32_32x32x16_bf16 v[114:129], v[196:199], v[212:215], v[114:129]
	ds_read_b128 v[220:223], v195 offset:0
	ds_read_b128 v[242:245], v161 offset:0
	v_mfma_f32_32x32x16_bf16 v[98:113], v[196:199], v[216:219], v[98:113]
	ds_read_b128 v[246:249], v161 offset:4096
	ds_read_b128 v[224:227], v195 offset:4096
	v_mfma_f32_32x32x16_bf16 v[82:97], v[200:203], v[212:215], v[82:97]
	ds_read_b128 v[228:231], v195 offset:8192
	ds_read_b128 v[238:241], v195 offset:12288
	v_mfma_f32_32x32x16_bf16 v[66:81], v[200:203], v[216:219], v[66:81]
	s_add_u32 m0, s58, 0x8000
	s_nop 0
	global_load_lds_dwordx4 v164, s[52:53]
	v_mfma_f32_32x32x16_bf16 v[50:65], v[204:207], v[212:215], v[50:65]
	s_add_u32 m0, s58, 0x8400
	s_nop 0
	global_load_lds_dwordx4 v165, s[52:53]
	v_mfma_f32_32x32x16_bf16 v[34:49], v[204:207], v[216:219], v[34:49]
	s_add_u32 m0, s58, 0x8800
	s_nop 0
	global_load_lds_dwordx4 v130, s[52:53]
	v_mfma_f32_32x32x16_bf16 v[18:33], v[208:211], v[212:215], v[18:33]
	s_add_u32 m0, s58, 0x8c00
	s_nop 0
	global_load_lds_dwordx4 v131, s[52:53]
	v_mfma_f32_32x32x16_bf16 v[2:17], v[208:211], v[216:219], v[2:17]
	s_waitcnt lgkmcnt(0)
	v_mfma_f32_32x32x16_bf16 v[114:129], v[220:223], v[242:245], v[114:129]
	ds_read_b128 v[196:199], v250 offset:0
	ds_read_b128 v[212:215], v162 offset:0
	v_mfma_f32_32x32x16_bf16 v[98:113], v[220:223], v[246:249], v[98:113]
	ds_read_b128 v[216:219], v162 offset:4096
	ds_read_b128 v[200:203], v250 offset:4096
	v_mfma_f32_32x32x16_bf16 v[82:97], v[224:227], v[242:245], v[82:97]
	ds_read_b128 v[204:207], v250 offset:8192
	ds_read_b128 v[208:211], v250 offset:12288
	v_mfma_f32_32x32x16_bf16 v[66:81], v[224:227], v[246:249], v[66:81]
	s_add_u32 m0, s59, 0x8000
	s_nop 0
	global_load_lds_dwordx4 v164, s[54:55]
	v_mfma_f32_32x32x16_bf16 v[50:65], v[228:231], v[242:245], v[50:65]
	s_add_u32 m0, s59, 0x8400
	s_nop 0
	global_load_lds_dwordx4 v165, s[54:55]
	v_mfma_f32_32x32x16_bf16 v[34:49], v[228:231], v[246:249], v[34:49]
	s_add_u32 m0, s59, 0x8800
	s_nop 0
	global_load_lds_dwordx4 v130, s[54:55]
	v_mfma_f32_32x32x16_bf16 v[18:33], v[238:241], v[242:245], v[18:33]
	s_add_u32 m0, s59, 0x8c00
	s_nop 0
	global_load_lds_dwordx4 v131, s[54:55]
	v_mfma_f32_32x32x16_bf16 v[2:17], v[238:241], v[246:249], v[2:17]
	s_waitcnt lgkmcnt(0)
	v_mfma_f32_32x32x16_bf16 v[114:129], v[196:199], v[212:215], v[114:129]
	ds_read_b128 v[220:223], v251 offset:0
	ds_read_b128 v[242:245], v163 offset:0
	v_mfma_f32_32x32x16_bf16 v[98:113], v[196:199], v[216:219], v[98:113]
	ds_read_b128 v[246:249], v163 offset:4096
	ds_read_b128 v[224:227], v251 offset:4096
	v_mfma_f32_32x32x16_bf16 v[82:97], v[200:203], v[212:215], v[82:97]
	ds_read_b128 v[228:231], v251 offset:8192
	ds_read_b128 v[238:241], v251 offset:12288
	v_mfma_f32_32x32x16_bf16 v[66:81], v[200:203], v[216:219], v[66:81]
	s_cmp_lt_u32 s56, s57
	s_cselect_b32 s60, 0x80, 0
	s_add_u32 s52, s52, s60
	s_addc_u32 s53, s53, 0
	s_add_u32 s54, s54, s60
	s_addc_u32 s55, s55, 0
	v_mfma_f32_32x32x16_bf16 v[50:65], v[204:207], v[212:215], v[50:65]
	v_mfma_f32_32x32x16_bf16 v[34:49], v[204:207], v[216:219], v[34:49]
	v_mfma_f32_32x32x16_bf16 v[18:33], v[208:211], v[212:215], v[18:33]
	v_mfma_f32_32x32x16_bf16 v[2:17], v[208:211], v[216:219], v[2:17]
	s_waitcnt lgkmcnt(0)
	v_mfma_f32_32x32x16_bf16 v[114:129], v[220:223], v[242:245], v[114:129]
	v_mfma_f32_32x32x16_bf16 v[98:113], v[220:223], v[246:249], v[98:113]
	v_mfma_f32_32x32x16_bf16 v[82:97], v[224:227], v[242:245], v[82:97]
	v_mfma_f32_32x32x16_bf16 v[66:81], v[224:227], v[246:249], v[66:81]
	v_mfma_f32_32x32x16_bf16 v[50:65], v[228:231], v[242:245], v[50:65]
	v_mfma_f32_32x32x16_bf16 v[34:49], v[228:231], v[246:249], v[34:49]
	v_mfma_f32_32x32x16_bf16 v[18:33], v[238:241], v[242:245], v[18:33]
	v_mfma_f32_32x32x16_bf16 v[2:17], v[238:241], v[246:249], v[2:17]
	s_waitcnt vmcnt(0)
	s_barrier
; #define MFMA32(a, b, c) __builtin_amdgcn_mfma_f32_32x32x16_bf16((a), (b), (c), 0, 0, 0)
; DI void gemm256(const char* a_u, unsigned a_voff, size_t astep, const char* b_u, unsigned b_voff, size_t bstep, int nk, char* smem, f32x16 (&acc)[4][2]) {
;     ...
;   for (int kt = 0; kt < nk; ++kt) {
;     const int cur = kt & 1, k2 = (kt + 2 < last) ? kt + 2 : last;
;     const char* S = smem + cur * 2 * T2;
;     char* D = smem + (cur ^ 1) * 2 * T2;
;     const char* an = a_u + (size_t)k2 * 128;
;     const char* bn = b_u + (size_t)k2 * 128;
; #pragma unroll
;     for (int s = 0; s < 4; ++s) {
;       bf16x8 a[4], b[2];
; #pragma unroll
;       for (int mi = 0; mi < 4; ++mi) a[mi] = *(const bf16x8*)(S + aoff + mi * 32 * LROW + s * 32);
; #pragma unroll
;       for (int ni = 0; ni < 2; ++ni) b[ni] = *(const bf16x8*)(S + boff + ni * 32 * LROW + s * 32);
;       *(u32x4*)(D + soff + s * 64 * LROW) = ra[s];
;       *(u32x4*)(D + T2 + soff + s * 64 * LROW) = rb[s];
;       ra[s] = *(const u32x4*)(an + s * astep + a_voff);
;       rb[s] = *(const u32x4*)(bn + s * bstep + b_voff);
; #pragma unroll
;       for (int mi = 0; mi < 4; ++mi)
; #pragma unroll
;         for (int ni = 0; ni < 2; ++ni) acc[mi][ni] = MFMA32(a[mi], b[ni], acc[mi][ni]);
;     }
;     __syncthreads();
;   }
	ds_read_b128 v[196:199], v194 offset:32768
	ds_read_b128 v[212:215], v160 offset:32768
	ds_read_b128 v[216:219], v160 offset:36864
	ds_read_b128 v[200:203], v194 offset:36864
	ds_read_b128 v[204:207], v194 offset:40960
	ds_read_b128 v[208:211], v194 offset:45056
	s_add_i32 s56, s56, 1
	s_waitcnt lgkmcnt(0)
	v_mfma_f32_32x32x16_bf16 v[114:129], v[196:199], v[212:215], v[114:129]
	ds_read_b128 v[220:223], v195 offset:32768
	ds_read_b128 v[242:245], v161 offset:32768
	v_mfma_f32_32x32x16_bf16 v[98:113], v[196:199], v[216:219], v[98:113]
	ds_read_b128 v[246:249], v161 offset:36864
	ds_read_b128 v[224:227], v195 offset:36864
	v_mfma_f32_32x32x16_bf16 v[82:97], v[200:203], v[212:215], v[82:97]
	ds_read_b128 v[228:231], v195 offset:40960
	ds_read_b128 v[238:241], v195 offset:45056
	v_mfma_f32_32x32x16_bf16 v[66:81], v[200:203], v[216:219], v[66:81]
	s_add_u32 m0, s58, 0x0
	s_nop 0
	global_load_lds_dwordx4 v164, s[52:53]
	v_mfma_f32_32x32x16_bf16 v[50:65], v[204:207], v[212:215], v[50:65]
	s_add_u32 m0, s58, 0x400
	s_nop 0
	global_load_lds_dwordx4 v165, s[52:53]
	v_mfma_f32_32x32x16_bf16 v[34:49], v[204:207], v[216:219], v[34:49]
	s_add_u32 m0, s58, 0x800
	s_nop 0
	global_load_lds_dwordx4 v130, s[52:53]
	v_mfma_f32_32x32x16_bf16 v[18:33], v[208:211], v[212:215], v[18:33]
	s_add_u32 m0, s58, 0xc00
	s_nop 0
	global_load_lds_dwordx4 v131, s[52:53]
	v_mfma_f32_32x32x16_bf16 v[2:17], v[208:211], v[216:219], v[2:17]
	s_waitcnt lgkmcnt(0)
	v_mfma_f32_32x32x16_bf16 v[114:129], v[220:223], v[242:245], v[114:129]
	ds_read_b128 v[196:199], v250 offset:32768
	ds_read_b128 v[212:215], v162 offset:32768
	v_mfma_f32_32x32x16_bf16 v[98:113], v[220:223], v[246:249], v[98:113]
	ds_read_b128 v[216:219], v162 offset:36864
	ds_read_b128 v[200:203], v250 offset:36864
	v_mfma_f32_32x32x16_bf16 v[82:97], v[224:227], v[242:245], v[82:97]
	ds_read_b128 v[204:207], v250 offset:40960
	ds_read_b128 v[208:211], v250 offset:45056
	v_mfma_f32_32x32x16_bf16 v[66:81], v[224:227], v[246:249], v[66:81]
	s_add_u32 m0, s59, 0x0
	s_nop 0
	global_load_lds_dwordx4 v164, s[54:55]
	v_mfma_f32_32x32x16_bf16 v[50:65], v[228:231], v[242:245], v[50:65]
	s_add_u32 m0, s59, 0x400
	s_nop 0
	global_load_lds_dwordx4 v165, s[54:55]
	v_mfma_f32_32x32x16_bf16 v[34:49], v[228:231], v[246:249], v[34:49]
	s_add_u32 m0, s59, 0x800
	s_nop 0
	global_load_lds_dwordx4 v130, s[54:55]
	v_mfma_f32_32x32x16_bf16 v[18:33], v[238:241], v[242:245], v[18:33]
	s_add_u32 m0, s59, 0xc00
	s_nop 0
	global_load_lds_dwordx4 v131, s[54:55]
	v_mfma_f32_32x32x16_bf16 v[2:17], v[238:241], v[246:249], v[2:17]
	s_waitcnt lgkmcnt(0)
	v_mfma_f32_32x32x16_bf16 v[114:129], v[196:199], v[212:215], v[114:129]
	ds_read_b128 v[220:223], v251 offset:32768
	ds_read_b128 v[242:245], v163 offset:32768
	v_mfma_f32_32x32x16_bf16 v[98:113], v[196:199], v[216:219], v[98:113]
	ds_read_b128 v[246:249], v163 offset:36864
	ds_read_b128 v[224:227], v251 offset:36864
	v_mfma_f32_32x32x16_bf16 v[82:97], v[200:203], v[212:215], v[82:97]
	ds_read_b128 v[228:231], v251 offset:40960
	ds_read_b128 v[238:241], v251 offset:45056
	v_mfma_f32_32x32x16_bf16 v[66:81], v[200:203], v[216:219], v[66:81]
	s_cmp_lt_u32 s56, s57
	s_cselect_b32 s60, 0x80, 0
	s_add_u32 s52, s52, s60
	s_addc_u32 s53, s53, 0
	s_add_u32 s54, s54, s60
	s_addc_u32 s55, s55, 0
	v_mfma_f32_32x32x16_bf16 v[50:65], v[204:207], v[212:215], v[50:65]
	v_mfma_f32_32x32x16_bf16 v[34:49], v[204:207], v[216:219], v[34:49]
	v_mfma_f32_32x32x16_bf16 v[18:33], v[208:211], v[212:215], v[18:33]
	v_mfma_f32_32x32x16_bf16 v[2:17], v[208:211], v[216:219], v[2:17]
	s_waitcnt lgkmcnt(0)
	v_mfma_f32_32x32x16_bf16 v[114:129], v[220:223], v[242:245], v[114:129]
	v_mfma_f32_32x32x16_bf16 v[98:113], v[220:223], v[246:249], v[98:113]
	v_mfma_f32_32x32x16_bf16 v[82:97], v[224:227], v[242:245], v[82:97]
	v_mfma_f32_32x32x16_bf16 v[66:81], v[224:227], v[246:249], v[66:81]
	v_mfma_f32_32x32x16_bf16 v[50:65], v[228:231], v[242:245], v[50:65]
	v_mfma_f32_32x32x16_bf16 v[34:49], v[228:231], v[246:249], v[34:49]
	v_mfma_f32_32x32x16_bf16 v[18:33], v[238:241], v[242:245], v[18:33]
	v_mfma_f32_32x32x16_bf16 v[2:17], v[238:241], v[246:249], v[2:17]
	s_waitcnt vmcnt(0)
	s_barrier
	ds_read_b128 v[196:199], v194 offset:0
	ds_read_b128 v[212:215], v160 offset:0
	ds_read_b128 v[216:219], v160 offset:4096
	ds_read_b128 v[200:203], v194 offset:4096
	ds_read_b128 v[204:207], v194 offset:8192
	ds_read_b128 v[208:211], v194 offset:12288
	s_cmp_lt_u32 s56, s57
	s_cbranch_scc1 .Lg_gateup_loop
	s_waitcnt lgkmcnt(0)
	s_nop 7
	s_nop 7
	s_branch .LBB0_1568

; DI int tid512() { int t = threadIdx.x; asm volatile("" : "+v"(t)); return t; }
; DI unsigned voff256(size_t ld) { const int t = tid512(); return (unsigned)(((size_t)(t >> 3) * ld + (t & 7) * 8) * 2); }
; DI void gemm256(const char* a_u, unsigned a_voff, size_t astep, const char* b_u, unsigned b_voff, size_t bstep, int nk, char* smem, f32x16 (&acc)[4][2]) {
;   asm volatile("" : "+s"(nk));
;   const int t = tid512(), lane = t & 63, w = t >> 6, wm = w >> 2, wn = w & 3, r = lane & 31, h = lane >> 5;
;   const int soff = (t >> 3) * LROW + (t & 7) * 16;
;   const int aoff = (128 * wm + r) * LROW + h * 16, boff = T2 + (64 * wn + r) * LROW + h * 16;
;   u32x4 ra[4], rb[4];
; #pragma unroll
;   for (int i = 0; i < 4; ++i) { ra[i] = *(const u32x4*)(a_u + i * astep + a_voff); rb[i] = *(const u32x4*)(b_u + i * bstep + b_voff); }
;   __syncthreads();
; #pragma unroll
;   for (int i = 0; i < 4; ++i) { *(u32x4*)(smem + soff + i * 64 * LROW) = ra[i]; *(u32x4*)(smem + T2 + soff + i * 64 * LROW) = rb[i]; }
;   const int last = nk - 1;
;   {
;     const int k1 = last < 1 ? last : 1;
; #pragma unroll
;     for (int i = 0; i < 4; ++i) { ra[i] = *(const u32x4*)(a_u + i * astep + k1 * 128 + a_voff); rb[i] = *(const u32x4*)(b_u + i * bstep + k1 * 128 + b_voff); }
;   }
;   __syncthreads();
; DI void down256(const Params& p, int layer, char* smem) {
;     ...
;     const int L = tile_of(i, 32 * 8);
;     if (L < 0) break;
;     int tm, tn; tile_mn(L, 32, 8, tm, tn);
;     f32x16 acc[4][2]; zero_acc256(acc);
;     gemm256((const char*)(HID + (size_t)(256 + tm * 256) * DFF), voff256(DFF), (size_t)128 * DFF, (const char*)(W + (size_t)(tn * 256) * DFF), voff256(DFF), (size_t)128 * DFF, DFF / 64, smem, acc);
.LBB0_1642:
	s_lshr_b32 s4, s6, 3
	s_and_b32 s4, s4, 0xffffffc
	s_sub_i32 s5, 32, s4
	s_min_i32 s5, s5, 4
	s_abs_i32 s11, s5
	v_cvt_f32_u32_e32 v2, s11
	s_sub_i32 s12, 0, s11
	s_and_b32 s7, s6, 31
	s_ashr_i32 s6, s5, 31
	v_rcp_iflag_f32_e32 v2, v2
	v_mov_b32_e32 v37, v181
	v_mul_f32_e32 v2, 0x4f7ffffe, v2
	v_cvt_u32_f32_e32 v2, v2
	s_nop 0
	v_readfirstlane_b32 s13, v2
	s_mul_i32 s12, s12, s13
	s_mul_hi_u32 s12, s13, s12
	s_add_i32 s13, s13, s12
	s_mul_hi_u32 s12, s7, s13
	s_mul_i32 s13, s12, s11
	s_sub_i32 s13, s7, s13
	s_add_i32 s14, s12, 1
	s_sub_i32 s15, s13, s11
	s_cmp_ge_u32 s13, s11
	s_cselect_b32 s12, s14, s12
	s_cselect_b32 s13, s15, s13
	s_add_i32 s14, s12, 1
	s_cmp_ge_u32 s13, s11
	s_cselect_b32 s11, s14, s12
	s_xor_b32 s11, s11, s6
	s_sub_i32 s6, s11, s6
	s_mul_i32 s5, s6, s5
	s_sub_i32 s5, s7, s5
	v_mov_b32_e32 v2, v0
	s_add_i32 s5, s5, s4
	s_lshl_b32 s11, s5, 8
	v_lshrrev_b32_e32 v3, 3, v2
	v_lshlrev_b32_e32 v2, 3, v2
	v_mul_lo_u32 v3, v3, s34
	s_addk_i32 s11, 0x100
	v_and_or_b32 v2, v2, 56, v3
	s_mul_i32 s4, s11, 0x2c00
	v_readlane_b32 s12, v254, 34
	v_lshlrev_b32_e32 v180, 1, v2
	v_mov_b32_e32 v2, v0
	s_mul_hi_u32 s5, s11, 0x2c00
	v_readlane_b32 s13, v254, 35
	s_add_u32 s4, s12, s4
	s_addc_u32 s5, s13, s5
	v_lshrrev_b32_e32 v3, 3, v2
	s_lshl_b32 s12, s6, 8
	s_mul_i32 s6, s6, 0x2c0000
	v_lshlrev_b32_e32 v2, 3, v2
	v_mul_lo_u32 v3, v3, s34
	s_mul_hi_i32 s7, s12, 0x2c00
	s_add_u32 s6, s8, s6
	v_and_or_b32 v2, v2, 56, v3
	v_lshl_add_u64 v[162:163], s[4:5], 0, v[180:181]
	s_addc_u32 s7, s9, s7
	v_lshlrev_b32_e32 v36, 1, v2
	v_add_co_u32_e32 v12, vcc, s26, v162
	v_lshl_add_u64 v[164:165], s[6:7], 0, v[36:37]
	s_nop 0
	v_addc_co_u32_e32 v13, vcc, 0, v163, vcc
	v_add_co_u32_e32 v16, vcc, s26, v164
	s_movk_i32 s13, 0x58
	v_mov_b32_e32 v2, v0
	v_addc_co_u32_e32 v17, vcc, 0, v165, vcc
	v_add_co_u32_e32 v20, vcc, s86, v162
	v_lshlrev_b32_e32 v4, 4, v2
	v_and_b32_e32 v38, 0x70, v4
	v_lshrrev_b32_e32 v132, 6, v0
	s_nop 0
	v_readfirstlane_b32 s61, v132
	v_and_b32_e32 v132, 63, v0
	v_and_b32_e32 v133, 31, v132
	v_lshrrev_b32_e32 v136, 5, v132
	v_bfe_u32 v137, v133, 1, 3
	v_lshlrev_b32_e32 v133, 7, v133
	s_lshr_b32 s60, s61, 2
	s_lshl_b32 s60, s60, 14
	s_add_i32 s60, s60, 16
	s_and_b32 s62, s61, 3
	s_lshl_b32 s62, s62, 13
	s_add_i32 s62, s62, 0x10010
	v_add_u32_e32 v194, 0, v136
	v_xor_b32_e32 v194, v194, v137
	v_lshl_add_u32 v194, v194, 4, v133
	v_add_u32_e32 v160, s62, v194
	v_add_u32_e32 v194, s60, v194
	v_add_u32_e32 v195, 2, v136
	v_xor_b32_e32 v195, v195, v137
	v_lshl_add_u32 v195, v195, 4, v133
	v_add_u32_e32 v161, s62, v195
	v_add_u32_e32 v195, s60, v195
	v_add_u32_e32 v250, 4, v136
	v_xor_b32_e32 v250, v250, v137
	v_lshl_add_u32 v250, v250, 4, v133
	v_add_u32_e32 v162, s62, v250
	v_add_u32_e32 v250, s60, v250
	v_add_u32_e32 v251, 6, v136
	v_xor_b32_e32 v251, v251, v137
	v_lshl_add_u32 v251, v251, 4, v133
	v_add_u32_e32 v163, s62, v251
	v_add_u32_e32 v251, s60, v251
	v_lshrrev_b32_e32 v133, 3, v132
	s_mov_b32 s60, 0x2c00
	v_mul_lo_u32 v133, v133, s60
	v_and_b32_e32 v136, 7, v132
	v_lshrrev_b32_e32 v137, 4, v132
	v_xor_b32_e32 v164, v137, v136
	v_lshl_add_u32 v164, v164, 4, v133
	v_add_u32_e32 v165, 4, v137
	v_xor_b32_e32 v165, v165, v136
	v_lshl_add_u32 v165, v165, 4, v133
	v_add_u32_e32 v165, 0x16000, v165
	v_xor_b32_e32 v130, v137, v136
	v_lshl_add_u32 v130, v130, 4, v133
	v_add_u32_e32 v130, 0x2c000, v130
	v_add_u32_e32 v131, 4, v137
	v_xor_b32_e32 v131, v131, v136
	v_lshl_add_u32 v131, v131, 4, v133
	v_add_u32_e32 v131, 0x42000, v131
	s_mul_i32 s60, s61, 0x58000
	s_add_u32 s52, s4, s60
	s_addc_u32 s53, s5, 0
	s_add_u32 s54, s6, s60
	s_addc_u32 s55, s7, 0
	s_lshl_b32 s58, s61, 12
	s_add_i32 s58, s58, 16
	s_add_i32 s59, s58, 0x10000
	s_mov_b32 s56, 0
	s_mov_b32 s57, 87
	s_barrier
	s_add_u32 m0, s58, 0x0
	s_nop 0
	global_load_lds_dwordx4 v164, s[52:53]
	s_add_u32 m0, s58, 0x400
	s_nop 0
	global_load_lds_dwordx4 v165, s[52:53]
	s_add_u32 m0, s58, 0x800
	s_nop 0
	global_load_lds_dwordx4 v130, s[52:53]
	s_add_u32 m0, s58, 0xc00
	s_nop 0
	global_load_lds_dwordx4 v131, s[52:53]
	s_add_u32 m0, s59, 0x0
	s_nop 0
	global_load_lds_dwordx4 v164, s[54:55]
	s_add_u32 m0, s59, 0x400
	s_nop 0
	global_load_lds_dwordx4 v165, s[54:55]
	s_add_u32 m0, s59, 0x800
	s_nop 0
	global_load_lds_dwordx4 v130, s[54:55]
	s_add_u32 m0, s59, 0xc00
	s_nop 0
	global_load_lds_dwordx4 v131, s[54:55]
	s_cmp_lt_u32 s56, s57
	s_cselect_b32 s60, 0x80, 0
	s_add_u32 s52, s52, s60
	s_addc_u32 s53, s53, 0
	s_add_u32 s54, s54, s60
	s_addc_u32 s55, s55, 0
	v_mov_b64_e32 v[114:115], 0
	v_mov_b64_e32 v[116:117], 0
	v_mov_b64_e32 v[118:119], 0
	v_mov_b64_e32 v[120:121], 0
	v_mov_b64_e32 v[122:123], 0
	v_mov_b64_e32 v[124:125], 0
	v_mov_b64_e32 v[126:127], 0
	v_mov_b64_e32 v[128:129], 0
	v_mov_b64_e32 v[98:99], 0
	v_mov_b64_e32 v[100:101], 0
	v_mov_b64_e32 v[102:103], 0
	v_mov_b64_e32 v[104:105], 0
	v_mov_b64_e32 v[106:107], 0
	v_mov_b64_e32 v[108:109], 0
	v_mov_b64_e32 v[110:111], 0
	v_mov_b64_e32 v[112:113], 0
	v_mov_b64_e32 v[82:83], 0
	v_mov_b64_e32 v[84:85], 0
	v_mov_b64_e32 v[86:87], 0
	v_mov_b64_e32 v[88:89], 0
	v_mov_b64_e32 v[90:91], 0
	v_mov_b64_e32 v[92:93], 0
	v_mov_b64_e32 v[94:95], 0
	v_mov_b64_e32 v[96:97], 0
	v_mov_b64_e32 v[66:67], 0
	v_mov_b64_e32 v[68:69], 0
	v_mov_b64_e32 v[70:71], 0
	v_mov_b64_e32 v[72:73], 0
	v_mov_b64_e32 v[74:75], 0
	v_mov_b64_e32 v[76:77], 0
	v_mov_b64_e32 v[78:79], 0
	v_mov_b64_e32 v[80:81], 0
	v_mov_b64_e32 v[50:51], 0
	v_mov_b64_e32 v[52:53], 0
	v_mov_b64_e32 v[54:55], 0
	v_mov_b64_e32 v[56:57], 0
	v_mov_b64_e32 v[58:59], 0
	v_mov_b64_e32 v[60:61], 0
	v_mov_b64_e32 v[62:63], 0
	v_mov_b64_e32 v[64:65], 0
	v_mov_b64_e32 v[34:35], 0
	v_mov_b64_e32 v[36:37], 0
	v_mov_b64_e32 v[38:39], 0
	v_mov_b64_e32 v[40:41], 0
	v_mov_b64_e32 v[42:43], 0
	v_mov_b64_e32 v[44:45], 0
	v_mov_b64_e32 v[46:47], 0
	v_mov_b64_e32 v[48:49], 0
	v_mov_b64_e32 v[18:19], 0
	v_mov_b64_e32 v[20:21], 0
	v_mov_b64_e32 v[22:23], 0
	v_mov_b64_e32 v[24:25], 0
	v_mov_b64_e32 v[26:27], 0
	v_mov_b64_e32 v[28:29], 0
	v_mov_b64_e32 v[30:31], 0
	v_mov_b64_e32 v[32:33], 0
	v_mov_b64_e32 v[2:3], 0
	v_mov_b64_e32 v[4:5], 0
	v_mov_b64_e32 v[6:7], 0
	v_mov_b64_e32 v[8:9], 0
	v_mov_b64_e32 v[10:11], 0
	v_mov_b64_e32 v[12:13], 0
	v_mov_b64_e32 v[14:15], 0
	v_mov_b64_e32 v[16:17], 0
	s_waitcnt vmcnt(0)
	s_barrier
	ds_read_b128 v[196:199], v194 offset:0
	ds_read_b128 v[212:215], v160 offset:0
	ds_read_b128 v[216:219], v160 offset:4096
	ds_read_b128 v[200:203], v194 offset:4096
	ds_read_b128 v[204:207], v194 offset:8192
	ds_read_b128 v[208:211], v194 offset:12288
